# SwiGLU / row-scale epilogues (P1 P3 P5 P10): the eight row-sum loads are issued before waves 0-3's realign barrier, not after it
# speedup vs baseline: 1.0184x; 1.0010x over previous
; #define PG8_BAR __builtin_amdgcn_s_barrier()
; template <class Epi, class Sched>
; __device__ __forceinline__ void gemm_phase(LAS unsigned char* lds, const Gemm g, const Sched& S, const Epi& E) {
;     ...
;         if (wr == 0) PG8_BAR;
;     __device__ __forceinline__ void operator()(const AccT& acc, const Unit& u, int wr, int wc, int fr, int fq) const {
;         const int row0 = u.pm * 256 + wr * 64 + fr, col0 = u.pn * 128 + wc * 32 + 8 * fq;
;         float rsv[2][4];
;         { f32x4 pv[2][4];
; #pragma unroll
;           for (int ai = 0; ai < 2; ++ai)
; #pragma unroll
;               for (int m = 0; m < 4; ++m) pv[ai][m] = *(const f32x4*)(ss + (size_t)(row0 + ai * 128 + m * 16) * 16 + fq * 4);
; #pragma unroll
;           for (int ai = 0; ai < 2; ++ai)
; #pragma unroll
;               for (int m = 0; m < 4; ++m) { const f32x4 a = pv[ai][m]; float t = (a[0] + a[1]) + (a[2] + a[3]); t = xsum_16_32(t); rsv[ai][m] = rsqrtf(t * (1.0f / DM) + EPS); } }
; #pragma unroll
;         for (int ai = 0; ai < 2; ++ai)
; #pragma unroll
;             for (int m = 0; m < 4; ++m) { const int row = row0 + ai * 128 + m * 16; const float rs = rsv[ai][m]; const float c1 = -rs * LOG2E, c2 = rs * rs;
;                 float a[8];
; #pragma unroll
;                 for (int n = 0; n < 2; ++n)
; #pragma unroll
;                     for (int j = 0; j < 4; ++j) { const float g_ = acc[ai][0][m][n][j]; a[n * 4 + j] = (g_ * acc[ai][1][m][n][j]) * (c2 * __builtin_amdgcn_rcpf(1.0f + __builtin_amdgcn_exp2f(g_ * c1))); }
.LBB0_179:
	v_lshl_add_u32 v180, s89, 8, v184
	v_ashrrev_i32_e32 v181, 31, v180
	v_lshlrev_b64 v[130:131], 6, v[180:181]
	v_or_b32_e32 v178, 16, v180
	v_lshl_add_u64 v[130:131], v[160:161], 0, v[130:131]
	v_ashrrev_i32_e32 v179, 31, v178
	global_load_dwordx4 v[188:191], v[130:131], off
	v_lshlrev_b64 v[130:131], 6, v[178:179]
	v_lshl_add_u64 v[130:131], v[160:161], 0, v[130:131]
	global_load_dwordx4 v[206:209], v[130:131], off
	v_or_b32_e32 v176, 32, v180
	v_ashrrev_i32_e32 v177, 31, v176
	v_lshlrev_b64 v[130:131], 6, v[176:177]
	v_or_b32_e32 v174, 48, v180
	v_lshl_add_u64 v[130:131], v[160:161], 0, v[130:131]
	v_ashrrev_i32_e32 v175, 31, v174
	global_load_dwordx4 v[150:153], v[130:131], off
	v_lshlrev_b64 v[130:131], 6, v[174:175]
	v_lshl_add_u64 v[130:131], v[160:161], 0, v[130:131]
	global_load_dwordx4 v[146:149], v[130:131], off
	v_add_u32_e32 v172, 0x80, v180
	v_ashrrev_i32_e32 v173, 31, v172
	v_lshlrev_b64 v[130:131], 6, v[172:173]
	v_add_u32_e32 v170, 0x90, v180
	v_lshl_add_u64 v[130:131], v[160:161], 0, v[130:131]
	v_ashrrev_i32_e32 v171, 31, v170
	global_load_dwordx4 v[142:145], v[130:131], off
	v_lshlrev_b64 v[130:131], 6, v[170:171]
	v_lshl_add_u64 v[130:131], v[160:161], 0, v[130:131]
	global_load_dwordx4 v[138:141], v[130:131], off
	v_add_u32_e32 v168, 0xa0, v180
	v_ashrrev_i32_e32 v169, 31, v168
	v_lshlrev_b64 v[130:131], 6, v[168:169]
	v_add_u32_e32 v166, 0xb0, v180
	v_lshl_add_u64 v[130:131], v[160:161], 0, v[130:131]
	v_ashrrev_i32_e32 v167, 31, v166
	global_load_dwordx4 v[134:137], v[130:131], off
	v_lshlrev_b64 v[130:131], 6, v[166:167]
	v_lshl_add_u64 v[130:131], v[160:161], 0, v[130:131]
	global_load_dwordx4 v[130:133], v[130:131], off
	s_and_b64 vcc, exec, s[58:59]
	s_cbranch_vccz .LBB0_181
	s_barrier
.LBB0_181:
	s_mov_b32 s0, 0x358637bd
	v_pk_mul_f32 v[120:121], v[120:121], v[116:117]
	v_pk_mul_f32 v[128:129], v[128:129], v[124:125]
	v_pk_mul_f32 v[112:113], v[112:113], v[108:109]
	v_pk_mul_f32 v[104:105], v[104:105], v[100:101]
	v_pk_mul_f32 v[96:97], v[96:97], v[92:93]
	v_pk_mul_f32 v[88:89], v[88:89], v[84:85]
	v_pk_mul_f32 v[80:81], v[80:81], v[76:77]
	v_pk_mul_f32 v[72:73], v[72:73], v[68:69]
	v_pk_mul_f32 v[64:65], v[64:65], v[60:61]
	v_pk_mul_f32 v[56:57], v[56:57], v[52:53]
	v_pk_mul_f32 v[48:49], v[48:49], v[44:45]
	v_pk_mul_f32 v[40:41], v[40:41], v[36:37]
	v_pk_mul_f32 v[32:33], v[32:33], v[28:29]
	v_pk_mul_f32 v[24:25], v[24:25], v[20:21]
	v_pk_mul_f32 v[16:17], v[16:17], v[12:13]
	v_pk_mul_f32 v[8:9], v[8:9], v[4:5]
	s_waitcnt vmcnt(0)
	v_mov_b32_e32 v182, v189
	v_mov_b32_e32 v183, v190
	v_mov_b32_e32 v189, v191
	v_pk_add_f32 v[182:183], v[182:183], v[188:189]
	v_mov_b32_e32 v190, v207
	v_pk_add_f32 v[182:183], v[182:183], v[182:183] op_sel:[0,1] op_sel_hi:[1,0]
	v_mov_b32_e32 v191, v208
	v_mov_b32_e32 v207, v209
	v_mov_b32_e32 v167, v182
	v_pk_add_f32 v[190:191], v[190:191], v[206:207]
	s_nop 0
	v_permlane16_swap_b32_e32 v182, v167
	v_pk_add_f32 v[190:191], v[190:191], v[190:191] op_sel:[0,1] op_sel_hi:[1,0]
	v_add_f32_e32 v183, v182, v167
	v_mov_b32_e32 v167, v190
	s_nop 1
	v_permlane16_swap_b32_e32 v190, v167
	v_add_f32_e32 v182, v190, v167
	v_mov_b32_e32 v189, v183
	v_mov_b32_e32 v188, v182
	s_nop 0
	v_permlane32_swap_b32_e32 v183, v189
	v_permlane32_swap_b32_e32 v182, v188
	v_pk_add_f32 v[188:189], v[182:183], v[188:189]
	v_mov_b64_e32 v[182:183], s[0:1]
	v_pk_fma_f32 v[188:189], v[188:189], s[4:5], v[182:183] op_sel_hi:[1,0,0]
	s_nop 0
	v_mul_f32_e32 v167, 0x4b800000, v189
	v_cmp_gt_f32_e64 s[40:41], s50, v189
	v_cmp_gt_f32_e32 vcc, s50, v188
	s_nop 0
	v_cndmask_b32_e64 v167, v189, v167, s[40:41]
	v_rsq_f32_e32 v167, v167
	v_mov_b32_e32 v189, v152
	v_mul_f32_e32 v169, 0x45800000, v167
	v_cndmask_b32_e64 v169, v167, v169, s[40:41]
	v_mul_f32_e32 v167, 0x4b800000, v188
	v_cndmask_b32_e32 v167, v188, v167, vcc
	v_mov_b32_e32 v188, v151
	v_mov_b32_e32 v151, v153
	v_pk_add_f32 v[150:151], v[188:189], v[150:151]
	v_mov_b32_e32 v188, v147
	v_mov_b32_e32 v189, v148
	v_mov_b32_e32 v147, v149
	v_pk_add_f32 v[146:147], v[188:189], v[146:147]
	v_pk_add_f32 v[150:151], v[150:151], v[150:151] op_sel:[0,1] op_sel_hi:[1,0]
	v_pk_add_f32 v[146:147], v[146:147], v[146:147] op_sel:[0,1] op_sel_hi:[1,0]
	v_mov_b32_e32 v151, v150
	v_mov_b32_e32 v147, v146
	s_nop 0
	v_permlane16_swap_b32_e32 v150, v151
	v_permlane16_swap_b32_e32 v146, v147
	v_add_f32_e32 v151, v150, v151
	v_add_f32_e32 v150, v146, v147
	v_mov_b32_e32 v153, v151
	v_mov_b32_e32 v152, v150
	s_nop 0
	v_permlane32_swap_b32_e32 v151, v153
	v_permlane32_swap_b32_e32 v150, v152
	v_pk_add_f32 v[146:147], v[150:151], v[152:153]
	v_rsq_f32_e32 v167, v167
	v_pk_fma_f32 v[146:147], v[146:147], s[4:5], v[182:183] op_sel_hi:[1,0,0]
	v_mov_b32_e32 v149, v144
	v_mul_f32_e32 v148, 0x4b800000, v147
	v_cmp_gt_f32_e64 s[40:41], s50, v147
	v_mul_f32_e32 v171, 0x45800000, v167
	v_cndmask_b32_e32 v167, v167, v171, vcc
	v_cndmask_b32_e64 v147, v147, v148, s[40:41]
	v_rsq_f32_e32 v147, v147
	v_cmp_gt_f32_e32 vcc, s50, v146
	v_mul_f32_e32 v148, 0x45800000, v147
	v_cndmask_b32_e64 v147, v147, v148, s[40:41]
	v_mul_f32_e32 v148, 0x4b800000, v146
	v_cndmask_b32_e32 v146, v146, v148, vcc
	v_rsq_f32_e32 v146, v146
	s_nop 0
	v_mul_f32_e32 v148, 0x45800000, v146
	v_cndmask_b32_e32 v146, v146, v148, vcc
	v_mov_b32_e32 v148, v143
	v_mov_b32_e32 v143, v145
	v_pk_add_f32 v[142:143], v[148:149], v[142:143]
	v_mov_b32_e32 v148, v139
	v_mov_b32_e32 v149, v140
	v_mov_b32_e32 v139, v141
	v_pk_add_f32 v[138:139], v[148:149], v[138:139]
	v_pk_add_f32 v[142:143], v[142:143], v[142:143] op_sel:[0,1] op_sel_hi:[1,0]
	v_pk_add_f32 v[138:139], v[138:139], v[138:139] op_sel:[0,1] op_sel_hi:[1,0]
; __device__ __forceinline__ unsigned cvtpk(float lo, float hi) { f32x2_t v = {lo, hi}; bf16x2_t b = __builtin_convertvector(v, bf16x2_t); return __builtin_bit_cast(unsigned, b); }
;     __device__ __forceinline__ void operator()(const AccT& acc, const Unit& u, int wr, int wc, int fr, int fq) const {
;     ...
;           for (int ai = 0; ai < 2; ++ai)
; #pragma unroll
;               for (int m = 0; m < 4; ++m) { const f32x4 a = pv[ai][m]; float t = (a[0] + a[1]) + (a[2] + a[3]); t = xsum_16_32(t); rsv[ai][m] = rsqrtf(t * (1.0f / DM) + EPS); } }
; #pragma unroll
;         for (int ai = 0; ai < 2; ++ai)
; #pragma unroll
;             for (int m = 0; m < 4; ++m) { const int row = row0 + ai * 128 + m * 16; const float rs = rsv[ai][m]; const float c1 = -rs * LOG2E, c2 = rs * rs;
;                 float a[8];
; #pragma unroll
;                 for (int n = 0; n < 2; ++n)
; #pragma unroll
;                     for (int j = 0; j < 4; ++j) { const float g_ = acc[ai][0][m][n][j]; a[n * 4 + j] = (g_ * acc[ai][1][m][n][j]) * (c2 * __builtin_amdgcn_rcpf(1.0f + __builtin_amdgcn_exp2f(g_ * c1))); }
;                 u32x4 w; w.x = cvtpk(a[0], a[1]); w.y = cvtpk(a[2], a[3]); w.z = cvtpk(a[4], a[5]); w.w = cvtpk(a[6], a[7]);
;                 *(u32x4*)(O + (size_t)row * DFF + col0) = w; }
	v_mov_b32_e32 v143, v142
	v_mov_b32_e32 v139, v138
	s_nop 0
	v_permlane16_swap_b32_e32 v142, v143
	v_permlane16_swap_b32_e32 v138, v139
	v_add_f32_e32 v143, v142, v143
	v_add_f32_e32 v142, v138, v139
	v_mov_b32_e32 v145, v143
	v_mov_b32_e32 v144, v142
	s_nop 0
	v_permlane32_swap_b32_e32 v143, v145
	v_permlane32_swap_b32_e32 v142, v144
	v_pk_add_f32 v[138:139], v[142:143], v[144:145]
	v_mov_b32_e32 v141, v136
	v_pk_fma_f32 v[138:139], v[138:139], s[4:5], v[182:183] op_sel_hi:[1,0,0]
	s_nop 0
	v_mul_f32_e32 v140, 0x4b800000, v139
	v_cmp_gt_f32_e64 s[40:41], s50, v139
	v_cmp_gt_f32_e32 vcc, s50, v138
	s_nop 0
	v_cndmask_b32_e64 v139, v139, v140, s[40:41]
	v_rsq_f32_e32 v139, v139
	s_nop 0
	v_mul_f32_e32 v140, 0x45800000, v139
	v_cndmask_b32_e64 v139, v139, v140, s[40:41]
	v_mul_f32_e32 v140, 0x4b800000, v138
	v_cndmask_b32_e32 v138, v138, v140, vcc
	v_rsq_f32_e32 v138, v138
	s_nop 0
	v_mul_f32_e32 v140, 0x45800000, v138
	v_cndmask_b32_e32 v138, v138, v140, vcc
	v_mov_b32_e32 v140, v135
	v_mov_b32_e32 v135, v137
	v_pk_add_f32 v[134:135], v[140:141], v[134:135]
	v_mov_b32_e32 v140, v131
	v_mov_b32_e32 v141, v132
	v_mov_b32_e32 v131, v133
	v_pk_add_f32 v[130:131], v[140:141], v[130:131]
	v_pk_add_f32 v[134:135], v[134:135], v[134:135] op_sel:[0,1] op_sel_hi:[1,0]
	v_pk_add_f32 v[130:131], v[130:131], v[130:131] op_sel:[0,1] op_sel_hi:[1,0]
	v_mov_b32_e32 v135, v134
	v_mov_b32_e32 v131, v130
	s_nop 0
	v_permlane16_swap_b32_e32 v134, v135
	v_permlane16_swap_b32_e32 v130, v131
	v_add_f32_e32 v135, v134, v135
	v_add_f32_e32 v134, v130, v131
	v_mov_b32_e32 v137, v135
	v_mov_b32_e32 v136, v134
	s_nop 0
	v_permlane32_swap_b32_e32 v135, v137
	v_permlane32_swap_b32_e32 v134, v136
	v_pk_add_f32 v[130:131], v[134:135], v[136:137]
	v_mul_f32_e32 v135, 0xbfb8aa3b, v169
	v_mul_f32_e32 v136, v122, v135
	v_mul_f32_e32 v137, v123, v135
	v_exp_f32_e32 v136, v136
	v_exp_f32_e32 v137, v137
	v_pk_fma_f32 v[130:131], v[130:131], s[4:5], v[182:183] op_sel_hi:[1,0,0]
	v_mul_f32_e32 v134, v169, v169
	v_add_f32_e32 v136, 1.0, v136
	v_add_f32_e32 v137, 1.0, v137
	v_rcp_f32_e32 v136, v136
	v_rcp_f32_e32 v137, v137
	v_mul_f32_e32 v132, 0x4b800000, v131
	v_cmp_gt_f32_e64 s[40:41], s50, v131
	v_pk_mul_f32 v[122:123], v[126:127], v[122:123]
	v_pk_mul_f32 v[126:127], v[134:135], v[136:137] op_sel_hi:[0,1]
	v_cndmask_b32_e64 v131, v131, v132, s[40:41]
	v_rsq_f32_e32 v131, v131
	v_pk_mul_f32 v[122:123], v[122:123], v[126:127]
	v_mul_f32_e32 v126, v114, v135
	v_mul_f32_e32 v127, v115, v135
	v_exp_f32_e32 v126, v126
	v_exp_f32_e32 v127, v127
	v_mul_f32_e32 v116, v116, v135
	v_mul_f32_e32 v117, v117, v135
	v_mul_f32_e32 v124, v124, v135
	v_mul_f32_e32 v125, v125, v135
	v_exp_f32_e32 v116, v116
	v_exp_f32_e32 v117, v117
	v_mul_f32_e32 v132, 0x45800000, v131
	v_exp_f32_e32 v124, v124
	v_exp_f32_e32 v125, v125
	v_cmp_gt_f32_e32 vcc, s50, v130
	v_cndmask_b32_e64 v131, v131, v132, s[40:41]
	v_mul_f32_e32 v132, 0x4b800000, v130
	v_cndmask_b32_e32 v130, v130, v132, vcc
	v_add_f32_e32 v126, 1.0, v126
	v_add_f32_e32 v127, 1.0, v127
	v_rsq_f32_e32 v130, v130
	v_rcp_f32_e32 v126, v126
	v_rcp_f32_e32 v127, v127
	v_add_f32_e32 v116, 1.0, v116
	v_add_f32_e32 v117, 1.0, v117
	v_add_f32_e32 v124, 1.0, v124
	v_add_f32_e32 v125, 1.0, v125
	v_rcp_f32_e32 v116, v116
	v_rcp_f32_e32 v117, v117
	v_rcp_f32_e32 v124, v124
	v_rcp_f32_e32 v125, v125
	v_mul_f32_e32 v132, 0x45800000, v130
	v_pk_mul_f32 v[114:115], v[118:119], v[114:115]
	v_pk_mul_f32 v[118:119], v[134:135], v[126:127] op_sel_hi:[0,1]
	v_cndmask_b32_e32 v130, v130, v132, vcc
	v_lshl_or_b32 v132, s14, 7, v186
	v_pk_mul_f32 v[114:115], v[114:115], v[118:119]
	v_pk_mul_f32 v[116:117], v[134:135], v[116:117] op_sel_hi:[0,1]
	v_ashrrev_i32_e32 v133, 31, v132
	v_pk_mul_f32 v[124:125], v[134:135], v[124:125] op_sel_hi:[0,1]
	v_pk_mul_f32 v[116:117], v[120:121], v[116:117]
	v_cvt_pk_bf16_f32 v120, v114, v115
	v_mov_b64_e32 v[114:115], s[70:71]
	v_pk_mul_f32 v[124:125], v[128:129], v[124:125]
	v_cvt_pk_bf16_f32 v118, v122, v123
	v_cvt_pk_bf16_f32 v121, v116, v117
	v_mad_i64_i32 v[122:123], s[0:1], v180, s97, v[114:115]
	v_lshlrev_b64 v[116:117], 1, v[132:133]
	v_cvt_pk_bf16_f32 v119, v124, v125
	v_lshl_add_u64 v[122:123], v[122:123], 0, v[116:117]
	global_store_dwordx4 v[122:123], v[118:121], off
	s_and_b64 vcc, exec, s[38:39]
	s_nop 0
	v_mul_f32_e32 v119, 0xbfb8aa3b, v167
	v_mul_f32_e32 v120, v106, v119
	v_mul_f32_e32 v121, v107, v119
	v_exp_f32_e32 v120, v120
	v_exp_f32_e32 v121, v121
	v_mul_f32_e32 v118, v167, v167
	v_pk_mul_f32 v[106:107], v[110:111], v[106:107]
	v_add_f32_e32 v120, 1.0, v120
	v_add_f32_e32 v121, 1.0, v121
	v_rcp_f32_e32 v120, v120
	v_rcp_f32_e32 v121, v121
	v_mul_f32_e32 v108, v108, v119
	v_mul_f32_e32 v109, v109, v119
	v_exp_f32_e32 v108, v108
	v_pk_mul_f32 v[110:111], v[118:119], v[120:121] op_sel_hi:[0,1]
	v_pk_mul_f32 v[106:107], v[106:107], v[110:111]
	v_mul_f32_e32 v110, v98, v119
	v_mul_f32_e32 v111, v99, v119
	v_exp_f32_e32 v110, v110
	v_exp_f32_e32 v111, v111
	v_pk_mul_f32 v[98:99], v[102:103], v[98:99]
	v_exp_f32_e32 v109, v109
	v_add_f32_e32 v110, 1.0, v110
	v_add_f32_e32 v111, 1.0, v111
	v_rcp_f32_e32 v110, v110
	v_rcp_f32_e32 v111, v111
	v_add_f32_e32 v108, 1.0, v108
	v_add_f32_e32 v109, 1.0, v109
	v_rcp_f32_e32 v108, v108
	v_pk_mul_f32 v[102:103], v[118:119], v[110:111] op_sel_hi:[0,1]
	v_pk_mul_f32 v[102:103], v[98:99], v[102:103]
	v_mul_f32_e32 v98, v100, v119
	v_mul_f32_e32 v99, v101, v119
	v_exp_f32_e32 v98, v98
	v_exp_f32_e32 v99, v99
	v_rcp_f32_e32 v109, v109
	v_cvt_pk_bf16_f32 v100, v102, v103
	v_add_f32_e32 v98, 1.0, v98
	v_add_f32_e32 v99, 1.0, v99
	v_rcp_f32_e32 v98, v98
	v_rcp_f32_e32 v99, v99
; __device__ __forceinline__ unsigned cvtpk(float lo, float hi) { f32x2_t v = {lo, hi}; bf16x2_t b = __builtin_convertvector(v, bf16x2_t); return __builtin_bit_cast(unsigned, b); }
;     __device__ __forceinline__ void operator()(const AccT& acc, const Unit& u, int wr, int wc, int fr, int fq) const {
;     ...
;             for (int m = 0; m < 4; ++m) { const int row = row0 + ai * 128 + m * 16; const float rs = rsv[ai][m]; const float c1 = -rs * LOG2E, c2 = rs * rs;
;                 float a[8];
; #pragma unroll
;                 for (int n = 0; n < 2; ++n)
; #pragma unroll
;                     for (int j = 0; j < 4; ++j) { const float g_ = acc[ai][0][m][n][j]; a[n * 4 + j] = (g_ * acc[ai][1][m][n][j]) * (c2 * __builtin_amdgcn_rcpf(1.0f + __builtin_amdgcn_exp2f(g_ * c1))); }
;                 u32x4 w; w.x = cvtpk(a[0], a[1]); w.y = cvtpk(a[2], a[3]); w.z = cvtpk(a[4], a[5]); w.w = cvtpk(a[6], a[7]);
;                 *(u32x4*)(O + (size_t)row * DFF + col0) = w; }
	v_pk_mul_f32 v[108:109], v[118:119], v[108:109] op_sel_hi:[0,1]
	v_pk_mul_f32 v[108:109], v[112:113], v[108:109]
	v_mad_i64_i32 v[102:103], s[0:1], v178, s97, v[114:115]
	v_pk_mul_f32 v[98:99], v[118:119], v[98:99] op_sel_hi:[0,1]
	v_pk_mul_f32 v[104:105], v[104:105], v[98:99]
	v_cvt_pk_bf16_f32 v98, v106, v107
	v_cvt_pk_bf16_f32 v99, v108, v109
	v_cvt_pk_bf16_f32 v101, v104, v105
	v_lshl_add_u64 v[102:103], v[102:103], 0, v[116:117]
	global_store_dwordx4 v[102:103], v[98:101], off
	s_nop 1
	v_mul_f32_e32 v99, 0xbfb8aa3b, v147
	v_mul_f32_e32 v100, v90, v99
	v_mul_f32_e32 v101, v91, v99
	v_exp_f32_e32 v100, v100
	v_exp_f32_e32 v101, v101
	v_mul_f32_e32 v98, v147, v147
	v_pk_mul_f32 v[90:91], v[94:95], v[90:91]
	v_add_f32_e32 v100, 1.0, v100
	v_add_f32_e32 v101, 1.0, v101
	v_rcp_f32_e32 v100, v100
	v_rcp_f32_e32 v101, v101
	v_mul_f32_e32 v92, v92, v99
	v_mul_f32_e32 v93, v93, v99
	v_exp_f32_e32 v92, v92
	v_pk_mul_f32 v[94:95], v[98:99], v[100:101] op_sel_hi:[0,1]
	v_pk_mul_f32 v[90:91], v[90:91], v[94:95]
	v_mul_f32_e32 v94, v82, v99
	v_mul_f32_e32 v95, v83, v99
	v_exp_f32_e32 v94, v94
	v_exp_f32_e32 v95, v95
	v_pk_mul_f32 v[82:83], v[86:87], v[82:83]
	v_exp_f32_e32 v93, v93
	v_add_f32_e32 v94, 1.0, v94
	v_add_f32_e32 v95, 1.0, v95
	v_rcp_f32_e32 v94, v94
	v_rcp_f32_e32 v95, v95
	v_add_f32_e32 v92, 1.0, v92
	v_add_f32_e32 v93, 1.0, v93
	v_rcp_f32_e32 v92, v92
	v_pk_mul_f32 v[86:87], v[98:99], v[94:95] op_sel_hi:[0,1]
	v_pk_mul_f32 v[86:87], v[82:83], v[86:87]
	v_mul_f32_e32 v82, v84, v99
	v_mul_f32_e32 v83, v85, v99
	v_exp_f32_e32 v82, v82
	v_exp_f32_e32 v83, v83
	v_rcp_f32_e32 v93, v93
	v_cvt_pk_bf16_f32 v84, v86, v87
	v_add_f32_e32 v82, 1.0, v82
	v_add_f32_e32 v83, 1.0, v83
	v_rcp_f32_e32 v82, v82
	v_rcp_f32_e32 v83, v83
	v_pk_mul_f32 v[92:93], v[98:99], v[92:93] op_sel_hi:[0,1]
	v_pk_mul_f32 v[92:93], v[96:97], v[92:93]
	v_mad_i64_i32 v[86:87], s[0:1], v176, s97, v[114:115]
	v_pk_mul_f32 v[82:83], v[98:99], v[82:83] op_sel_hi:[0,1]
	v_pk_mul_f32 v[88:89], v[88:89], v[82:83]
	v_cvt_pk_bf16_f32 v82, v90, v91
	v_cvt_pk_bf16_f32 v83, v92, v93
	v_cvt_pk_bf16_f32 v85, v88, v89
	v_lshl_add_u64 v[86:87], v[86:87], 0, v[116:117]
	global_store_dwordx4 v[86:87], v[82:85], off
	s_nop 1
	v_mul_f32_e32 v83, 0xbfb8aa3b, v146
	v_mul_f32_e32 v84, v74, v83
	v_mul_f32_e32 v85, v75, v83
	v_exp_f32_e32 v84, v84
	v_exp_f32_e32 v85, v85
	v_mul_f32_e32 v82, v146, v146
	v_pk_mul_f32 v[74:75], v[78:79], v[74:75]
	v_add_f32_e32 v84, 1.0, v84
	v_add_f32_e32 v85, 1.0, v85
	v_rcp_f32_e32 v84, v84
	v_rcp_f32_e32 v85, v85
	v_mul_f32_e32 v76, v76, v83
	v_mul_f32_e32 v77, v77, v83
	v_exp_f32_e32 v76, v76
	v_pk_mul_f32 v[78:79], v[82:83], v[84:85] op_sel_hi:[0,1]
	v_pk_mul_f32 v[74:75], v[74:75], v[78:79]
	v_mul_f32_e32 v78, v66, v83
	v_mul_f32_e32 v79, v67, v83
	v_exp_f32_e32 v78, v78
	v_exp_f32_e32 v79, v79
	v_pk_mul_f32 v[66:67], v[70:71], v[66:67]
	v_exp_f32_e32 v77, v77
	v_add_f32_e32 v78, 1.0, v78
	v_add_f32_e32 v79, 1.0, v79
	v_rcp_f32_e32 v78, v78
	v_rcp_f32_e32 v79, v79
	v_add_f32_e32 v76, 1.0, v76
	v_add_f32_e32 v77, 1.0, v77
	v_rcp_f32_e32 v76, v76
	v_pk_mul_f32 v[70:71], v[82:83], v[78:79] op_sel_hi:[0,1]
	v_pk_mul_f32 v[70:71], v[66:67], v[70:71]
	v_mul_f32_e32 v66, v68, v83
	v_mul_f32_e32 v67, v69, v83
	v_exp_f32_e32 v66, v66
	v_exp_f32_e32 v67, v67
	v_rcp_f32_e32 v77, v77
	v_cvt_pk_bf16_f32 v68, v70, v71
	v_add_f32_e32 v66, 1.0, v66
	v_add_f32_e32 v67, 1.0, v67
	v_rcp_f32_e32 v66, v66
	v_rcp_f32_e32 v67, v67
	v_pk_mul_f32 v[76:77], v[82:83], v[76:77] op_sel_hi:[0,1]
	v_pk_mul_f32 v[76:77], v[80:81], v[76:77]
	v_mad_i64_i32 v[70:71], s[0:1], v174, s97, v[114:115]
	v_pk_mul_f32 v[66:67], v[82:83], v[66:67] op_sel_hi:[0,1]
	v_pk_mul_f32 v[72:73], v[72:73], v[66:67]
	v_cvt_pk_bf16_f32 v66, v74, v75
	v_cvt_pk_bf16_f32 v67, v76, v77
	v_cvt_pk_bf16_f32 v69, v72, v73
	v_lshl_add_u64 v[70:71], v[70:71], 0, v[116:117]
	global_store_dwordx4 v[70:71], v[66:69], off
	s_nop 1
	v_mul_f32_e32 v67, 0xbfb8aa3b, v139
	v_mul_f32_e32 v68, v58, v67
	v_mul_f32_e32 v69, v59, v67
	v_exp_f32_e32 v68, v68
	v_exp_f32_e32 v69, v69
	v_mul_f32_e32 v66, v139, v139
	v_pk_mul_f32 v[58:59], v[62:63], v[58:59]
	v_add_f32_e32 v68, 1.0, v68
	v_add_f32_e32 v69, 1.0, v69
	v_rcp_f32_e32 v68, v68
	v_rcp_f32_e32 v69, v69
	v_mul_f32_e32 v60, v60, v67
	v_mul_f32_e32 v61, v61, v67
	v_exp_f32_e32 v60, v60
	v_pk_mul_f32 v[62:63], v[66:67], v[68:69] op_sel_hi:[0,1]
	v_pk_mul_f32 v[58:59], v[58:59], v[62:63]
	v_mul_f32_e32 v62, v50, v67
	v_mul_f32_e32 v63, v51, v67
	v_exp_f32_e32 v62, v62
	v_exp_f32_e32 v63, v63
	v_pk_mul_f32 v[50:51], v[54:55], v[50:51]
	v_exp_f32_e32 v61, v61
	v_add_f32_e32 v62, 1.0, v62
	v_add_f32_e32 v63, 1.0, v63
	v_rcp_f32_e32 v62, v62
	v_rcp_f32_e32 v63, v63
	v_add_f32_e32 v60, 1.0, v60
	v_add_f32_e32 v61, 1.0, v61
	v_rcp_f32_e32 v60, v60
	v_pk_mul_f32 v[54:55], v[66:67], v[62:63] op_sel_hi:[0,1]
	v_pk_mul_f32 v[54:55], v[50:51], v[54:55]
	v_mul_f32_e32 v50, v52, v67
	v_mul_f32_e32 v51, v53, v67
	v_exp_f32_e32 v50, v50
	v_exp_f32_e32 v51, v51
	v_rcp_f32_e32 v61, v61
	v_cvt_pk_bf16_f32 v52, v54, v55
	v_add_f32_e32 v50, 1.0, v50
	v_add_f32_e32 v51, 1.0, v51
	v_rcp_f32_e32 v50, v50
	v_rcp_f32_e32 v51, v51
	v_pk_mul_f32 v[60:61], v[66:67], v[60:61] op_sel_hi:[0,1]
	v_pk_mul_f32 v[60:61], v[64:65], v[60:61]
	v_mad_i64_i32 v[54:55], s[0:1], v172, s97, v[114:115]
	v_pk_mul_f32 v[50:51], v[66:67], v[50:51] op_sel_hi:[0,1]
	v_pk_mul_f32 v[56:57], v[56:57], v[50:51]
; __device__ __forceinline__ unsigned cvtpk(float lo, float hi) { f32x2_t v = {lo, hi}; bf16x2_t b = __builtin_convertvector(v, bf16x2_t); return __builtin_bit_cast(unsigned, b); }
;     __device__ __forceinline__ void operator()(const AccT& acc, const Unit& u, int wr, int wc, int fr, int fq) const {
;     ...
;             for (int m = 0; m < 4; ++m) { const int row = row0 + ai * 128 + m * 16; const float rs = rsv[ai][m]; const float c1 = -rs * LOG2E, c2 = rs * rs;
;                 float a[8];
; #pragma unroll
;                 for (int n = 0; n < 2; ++n)
; #pragma unroll
;                     for (int j = 0; j < 4; ++j) { const float g_ = acc[ai][0][m][n][j]; a[n * 4 + j] = (g_ * acc[ai][1][m][n][j]) * (c2 * __builtin_amdgcn_rcpf(1.0f + __builtin_amdgcn_exp2f(g_ * c1))); }
;                 u32x4 w; w.x = cvtpk(a[0], a[1]); w.y = cvtpk(a[2], a[3]); w.z = cvtpk(a[4], a[5]); w.w = cvtpk(a[6], a[7]);
;                 *(u32x4*)(O + (size_t)row * DFF + col0) = w; }
	v_cvt_pk_bf16_f32 v50, v58, v59
	v_cvt_pk_bf16_f32 v51, v60, v61
	v_cvt_pk_bf16_f32 v53, v56, v57
	v_lshl_add_u64 v[54:55], v[54:55], 0, v[116:117]
	global_store_dwordx4 v[54:55], v[50:53], off
	s_nop 1
	v_mul_f32_e32 v51, 0xbfb8aa3b, v138
	v_mul_f32_e32 v52, v42, v51
	v_mul_f32_e32 v53, v43, v51
	v_exp_f32_e32 v52, v52
	v_exp_f32_e32 v53, v53
	v_mul_f32_e32 v50, v138, v138
	v_pk_mul_f32 v[42:43], v[46:47], v[42:43]
	v_add_f32_e32 v52, 1.0, v52
	v_add_f32_e32 v53, 1.0, v53
	v_rcp_f32_e32 v52, v52
	v_rcp_f32_e32 v53, v53
	v_mul_f32_e32 v44, v44, v51
	v_mul_f32_e32 v45, v45, v51
	v_exp_f32_e32 v44, v44
	v_pk_mul_f32 v[46:47], v[50:51], v[52:53] op_sel_hi:[0,1]
	v_pk_mul_f32 v[42:43], v[42:43], v[46:47]
	v_mul_f32_e32 v46, v34, v51
	v_mul_f32_e32 v47, v35, v51
	v_exp_f32_e32 v46, v46
	v_exp_f32_e32 v47, v47
	v_pk_mul_f32 v[34:35], v[38:39], v[34:35]
	v_exp_f32_e32 v45, v45
	v_add_f32_e32 v46, 1.0, v46
	v_add_f32_e32 v47, 1.0, v47
	v_rcp_f32_e32 v46, v46
	v_rcp_f32_e32 v47, v47
	v_add_f32_e32 v44, 1.0, v44
	v_add_f32_e32 v45, 1.0, v45
	v_rcp_f32_e32 v44, v44
	v_pk_mul_f32 v[38:39], v[50:51], v[46:47] op_sel_hi:[0,1]
	v_pk_mul_f32 v[38:39], v[34:35], v[38:39]
	v_mul_f32_e32 v34, v36, v51
	v_mul_f32_e32 v35, v37, v51
	v_exp_f32_e32 v34, v34
	v_exp_f32_e32 v35, v35
	v_rcp_f32_e32 v45, v45
	v_cvt_pk_bf16_f32 v36, v38, v39
	v_add_f32_e32 v34, 1.0, v34
	v_add_f32_e32 v35, 1.0, v35
	v_rcp_f32_e32 v34, v34
	v_rcp_f32_e32 v35, v35
	v_pk_mul_f32 v[44:45], v[50:51], v[44:45] op_sel_hi:[0,1]
	v_pk_mul_f32 v[44:45], v[48:49], v[44:45]
	v_mad_i64_i32 v[38:39], s[0:1], v170, s97, v[114:115]
	v_pk_mul_f32 v[34:35], v[50:51], v[34:35] op_sel_hi:[0,1]
	v_pk_mul_f32 v[40:41], v[40:41], v[34:35]
	v_cvt_pk_bf16_f32 v34, v42, v43
	v_cvt_pk_bf16_f32 v35, v44, v45
	v_cvt_pk_bf16_f32 v37, v40, v41
	v_lshl_add_u64 v[38:39], v[38:39], 0, v[116:117]
	global_store_dwordx4 v[38:39], v[34:37], off
	s_nop 1
	v_mul_f32_e32 v35, 0xbfb8aa3b, v131
	v_mul_f32_e32 v36, v26, v35
	v_mul_f32_e32 v37, v27, v35
	v_exp_f32_e32 v36, v36
	v_exp_f32_e32 v37, v37
	v_mul_f32_e32 v34, v131, v131
	v_pk_mul_f32 v[26:27], v[30:31], v[26:27]
	v_add_f32_e32 v36, 1.0, v36
	v_add_f32_e32 v37, 1.0, v37
	v_rcp_f32_e32 v36, v36
	v_rcp_f32_e32 v37, v37
	v_mul_f32_e32 v28, v28, v35
	v_mul_f32_e32 v29, v29, v35
	v_exp_f32_e32 v28, v28
	v_pk_mul_f32 v[30:31], v[34:35], v[36:37] op_sel_hi:[0,1]
	v_pk_mul_f32 v[26:27], v[26:27], v[30:31]
	v_mul_f32_e32 v30, v18, v35
	v_mul_f32_e32 v31, v19, v35
	v_exp_f32_e32 v30, v30
	v_exp_f32_e32 v31, v31
	v_pk_mul_f32 v[18:19], v[22:23], v[18:19]
	v_exp_f32_e32 v29, v29
	v_add_f32_e32 v30, 1.0, v30
	v_add_f32_e32 v31, 1.0, v31
	v_rcp_f32_e32 v30, v30
	v_rcp_f32_e32 v31, v31
	v_add_f32_e32 v28, 1.0, v28
	v_add_f32_e32 v29, 1.0, v29
	v_rcp_f32_e32 v28, v28
	v_pk_mul_f32 v[22:23], v[34:35], v[30:31] op_sel_hi:[0,1]
	v_pk_mul_f32 v[22:23], v[18:19], v[22:23]
	v_mul_f32_e32 v18, v20, v35
	v_mul_f32_e32 v19, v21, v35
	v_exp_f32_e32 v18, v18
	v_exp_f32_e32 v19, v19
	v_rcp_f32_e32 v29, v29
	v_cvt_pk_bf16_f32 v20, v22, v23
	v_add_f32_e32 v18, 1.0, v18
	v_add_f32_e32 v19, 1.0, v19
	v_rcp_f32_e32 v18, v18
	v_rcp_f32_e32 v19, v19
	v_pk_mul_f32 v[28:29], v[34:35], v[28:29] op_sel_hi:[0,1]
	v_pk_mul_f32 v[28:29], v[32:33], v[28:29]
	v_mad_i64_i32 v[22:23], s[0:1], v168, s97, v[114:115]
	v_pk_mul_f32 v[18:19], v[34:35], v[18:19] op_sel_hi:[0,1]
	v_pk_mul_f32 v[24:25], v[24:25], v[18:19]
	v_cvt_pk_bf16_f32 v18, v26, v27
	v_cvt_pk_bf16_f32 v19, v28, v29
	v_cvt_pk_bf16_f32 v21, v24, v25
	v_lshl_add_u64 v[22:23], v[22:23], 0, v[116:117]
	global_store_dwordx4 v[22:23], v[18:21], off
	s_nop 1
	v_mul_f32_e32 v19, 0xbfb8aa3b, v130
	v_mul_f32_e32 v20, v10, v19
	v_mul_f32_e32 v21, v11, v19
	v_exp_f32_e32 v20, v20
	v_exp_f32_e32 v21, v21
	v_mul_f32_e32 v18, v130, v130
	v_pk_mul_f32 v[10:11], v[14:15], v[10:11]
	v_add_f32_e32 v20, 1.0, v20
	v_add_f32_e32 v21, 1.0, v21
	v_rcp_f32_e32 v20, v20
	v_rcp_f32_e32 v21, v21
	v_mul_f32_e32 v12, v12, v19
	v_mul_f32_e32 v13, v13, v19
	v_exp_f32_e32 v12, v12
	v_pk_mul_f32 v[14:15], v[18:19], v[20:21] op_sel_hi:[0,1]
	v_pk_mul_f32 v[10:11], v[10:11], v[14:15]
	v_mul_f32_e32 v14, v2, v19
	v_mul_f32_e32 v15, v3, v19
	v_exp_f32_e32 v14, v14
	v_exp_f32_e32 v15, v15
	v_pk_mul_f32 v[2:3], v[6:7], v[2:3]
	v_exp_f32_e32 v13, v13
	v_add_f32_e32 v14, 1.0, v14
	v_add_f32_e32 v15, 1.0, v15
	v_rcp_f32_e32 v14, v14
	v_rcp_f32_e32 v15, v15
	v_add_f32_e32 v12, 1.0, v12
	v_add_f32_e32 v13, 1.0, v13
	v_rcp_f32_e32 v12, v12
	v_pk_mul_f32 v[6:7], v[18:19], v[14:15] op_sel_hi:[0,1]
	v_pk_mul_f32 v[6:7], v[2:3], v[6:7]
	v_mul_f32_e32 v2, v4, v19
	v_mul_f32_e32 v3, v5, v19
	v_exp_f32_e32 v2, v2
	v_exp_f32_e32 v3, v3
	v_rcp_f32_e32 v13, v13
	v_cvt_pk_bf16_f32 v4, v6, v7
	v_add_f32_e32 v2, 1.0, v2
	v_add_f32_e32 v3, 1.0, v3
	v_rcp_f32_e32 v2, v2
	v_rcp_f32_e32 v3, v3
	v_pk_mul_f32 v[12:13], v[18:19], v[12:13] op_sel_hi:[0,1]
	v_pk_mul_f32 v[12:13], v[16:17], v[12:13]
	v_mad_i64_i32 v[6:7], s[0:1], v166, s97, v[114:115]
	v_pk_mul_f32 v[2:3], v[18:19], v[2:3] op_sel_hi:[0,1]
	v_pk_mul_f32 v[8:9], v[8:9], v[2:3]
	v_cvt_pk_bf16_f32 v2, v10, v11
	v_cvt_pk_bf16_f32 v3, v12, v13
	v_cvt_pk_bf16_f32 v5, v8, v9
	v_lshl_add_u64 v[6:7], v[6:7], 0, v[116:117]
	s_mov_b64 s[0:1], -1
	global_store_dwordx4 v[6:7], v[2:5], off
	s_cbranch_vccnz .LBB0_169
	s_andn2_b64 vcc, exec, s[54:55]
	s_cbranch_vccnz .LBB0_168
	s_barrier
	s_branch .LBB0_168

; #define PG8_BAR __builtin_amdgcn_s_barrier()
; template <class Epi, class Sched>
; __device__ __forceinline__ void gemm_phase(LAS unsigned char* lds, const Gemm g, const Sched& S, const Epi& E) {
;     ...
;         if (wr == 0) PG8_BAR;
;     __device__ __forceinline__ void operator()(const AccT& acc, const Unit& u, int wr, int wc, int fr, int fq) const {
;         const int row0 = u.pm * 256 + wr * 64 + fr, col0 = u.pn * 256 + wc * 32 + 8 * fq;
;         float rsv[2][4];
;         { f32x4 pv[2][4];
; #pragma unroll
;           for (int ai = 0; ai < 2; ++ai)
; #pragma unroll
;               for (int m = 0; m < 4; ++m) pv[ai][m] = *(const f32x4*)(ss + (size_t)(row0 + ai * 128 + m * 16) * 16 + fq * 4);
; #pragma unroll
;           for (int ai = 0; ai < 2; ++ai)
; #pragma unroll
;               for (int m = 0; m < 4; ++m) { const f32x4 a = pv[ai][m]; float t = (a[0] + a[1]) + (a[2] + a[3]); t = xsum_16_32(t); rsv[ai][m] = rsqrtf(t * (1.0f / DM) + EPS); } }
.LBB0_429:
	v_lshl_add_u32 v180, s90, 8, v183
	v_ashrrev_i32_e32 v181, 31, v180
	v_lshlrev_b64 v[130:131], 6, v[180:181]
	v_or_b32_e32 v178, 16, v180
	v_lshl_add_u64 v[130:131], v[160:161], 0, v[130:131]
	v_ashrrev_i32_e32 v179, 31, v178
	global_load_dwordx4 v[190:193], v[130:131], off
	v_lshlrev_b64 v[130:131], 6, v[178:179]
	v_lshl_add_u64 v[130:131], v[160:161], 0, v[130:131]
	global_load_dwordx4 v[206:209], v[130:131], off
	v_or_b32_e32 v176, 32, v180
	v_ashrrev_i32_e32 v177, 31, v176
	v_lshlrev_b64 v[130:131], 6, v[176:177]
	v_or_b32_e32 v174, 48, v180
	v_lshl_add_u64 v[130:131], v[160:161], 0, v[130:131]
	v_ashrrev_i32_e32 v175, 31, v174
	global_load_dwordx4 v[150:153], v[130:131], off
	v_lshlrev_b64 v[130:131], 6, v[174:175]
	v_lshl_add_u64 v[130:131], v[160:161], 0, v[130:131]
	global_load_dwordx4 v[146:149], v[130:131], off
	v_add_u32_e32 v172, 0x80, v180
	v_ashrrev_i32_e32 v173, 31, v172
	v_lshlrev_b64 v[130:131], 6, v[172:173]
	v_add_u32_e32 v170, 0x90, v180
	v_lshl_add_u64 v[130:131], v[160:161], 0, v[130:131]
	v_ashrrev_i32_e32 v171, 31, v170
	global_load_dwordx4 v[142:145], v[130:131], off
	v_lshlrev_b64 v[130:131], 6, v[170:171]
	v_lshl_add_u64 v[130:131], v[160:161], 0, v[130:131]
	global_load_dwordx4 v[138:141], v[130:131], off
	v_add_u32_e32 v168, 0xa0, v180
	v_ashrrev_i32_e32 v169, 31, v168
	v_lshlrev_b64 v[130:131], 6, v[168:169]
	v_add_u32_e32 v166, 0xb0, v180
	v_lshl_add_u64 v[130:131], v[160:161], 0, v[130:131]
	v_ashrrev_i32_e32 v167, 31, v166
	global_load_dwordx4 v[134:137], v[130:131], off
	v_lshlrev_b64 v[130:131], 6, v[166:167]
	v_lshl_add_u64 v[130:131], v[160:161], 0, v[130:131]
	global_load_dwordx4 v[130:133], v[130:131], off
	s_and_b64 vcc, exec, s[62:63]
	s_cbranch_vccz .LBB0_431
	s_barrier
.LBB0_431:
	s_mov_b32 s0, 0x358637bd
	s_waitcnt vmcnt(0)
	v_mov_b32_e32 v186, v191
	v_mov_b32_e32 v187, v192
	v_mov_b32_e32 v191, v193
	v_pk_add_f32 v[186:187], v[186:187], v[190:191]
	v_mov_b32_e32 v192, v207
	v_pk_add_f32 v[186:187], v[186:187], v[186:187] op_sel:[0,1] op_sel_hi:[1,0]
	v_mov_b32_e32 v193, v208
	v_mov_b32_e32 v207, v209
	v_mov_b32_e32 v167, v186
	v_pk_add_f32 v[192:193], v[192:193], v[206:207]
	s_nop 0
	v_permlane16_swap_b32_e32 v186, v167
	v_pk_add_f32 v[192:193], v[192:193], v[192:193] op_sel:[0,1] op_sel_hi:[1,0]
	v_add_f32_e32 v187, v186, v167
	v_mov_b32_e32 v167, v192
	s_nop 1
	v_permlane16_swap_b32_e32 v192, v167
	v_add_f32_e32 v186, v192, v167
	v_mov_b32_e32 v191, v187
	v_mov_b32_e32 v190, v186
	s_nop 0
	v_permlane32_swap_b32_e32 v187, v191
	v_permlane32_swap_b32_e32 v186, v190
	v_pk_add_f32 v[190:191], v[186:187], v[190:191]
	v_mov_b64_e32 v[186:187], s[0:1]
	v_pk_fma_f32 v[190:191], v[190:191], s[4:5], v[186:187] op_sel_hi:[1,0,0]
	s_nop 0
	v_mul_f32_e32 v167, 0x4b800000, v191
	v_cmp_gt_f32_e64 s[46:47], s50, v191
	v_cmp_gt_f32_e32 vcc, s50, v190
	s_nop 0
	v_cndmask_b32_e64 v167, v191, v167, s[46:47]
	v_rsq_f32_e32 v167, v167
	v_mov_b32_e32 v191, v152
	v_mul_f32_e32 v169, 0x45800000, v167
	v_cndmask_b32_e64 v184, v167, v169, s[46:47]
	v_mul_f32_e32 v167, 0x4b800000, v190
	v_cndmask_b32_e32 v167, v190, v167, vcc
	v_mov_b32_e32 v190, v151
	v_mov_b32_e32 v151, v153
	v_pk_add_f32 v[150:151], v[190:191], v[150:151]
	v_mov_b32_e32 v190, v147
	v_mov_b32_e32 v191, v148
	v_mov_b32_e32 v147, v149
	v_pk_add_f32 v[146:147], v[190:191], v[146:147]
	v_pk_add_f32 v[150:151], v[150:151], v[150:151] op_sel:[0,1] op_sel_hi:[1,0]
	v_pk_add_f32 v[146:147], v[146:147], v[146:147] op_sel:[0,1] op_sel_hi:[1,0]
	v_mov_b32_e32 v151, v150
	v_mov_b32_e32 v147, v146
	s_nop 0
	v_permlane16_swap_b32_e32 v150, v151
	v_permlane16_swap_b32_e32 v146, v147
	v_add_f32_e32 v151, v150, v151
	v_add_f32_e32 v150, v146, v147
	v_mov_b32_e32 v153, v151
	v_mov_b32_e32 v152, v150
	s_nop 0
	v_permlane32_swap_b32_e32 v151, v153
	v_permlane32_swap_b32_e32 v150, v152
	v_pk_add_f32 v[146:147], v[150:151], v[152:153]
	v_mov_b32_e32 v150, v143
	v_mov_b32_e32 v151, v144
	v_mov_b32_e32 v143, v145
	v_pk_add_f32 v[142:143], v[150:151], v[142:143]
	v_mov_b32_e32 v150, v139
	v_mov_b32_e32 v151, v140
	v_mov_b32_e32 v139, v141
	v_pk_add_f32 v[138:139], v[150:151], v[138:139]
	v_pk_add_f32 v[142:143], v[142:143], v[142:143] op_sel:[0,1] op_sel_hi:[1,0]
	v_pk_add_f32 v[138:139], v[138:139], v[138:139] op_sel:[0,1] op_sel_hi:[1,0]
	v_mov_b32_e32 v143, v142
	v_mov_b32_e32 v139, v138
	s_nop 0
	v_permlane16_swap_b32_e32 v142, v143
	v_permlane16_swap_b32_e32 v138, v139
	v_add_f32_e32 v143, v142, v143
	v_add_f32_e32 v142, v138, v139
	v_mov_b32_e32 v145, v143
	v_mov_b32_e32 v144, v142
	s_nop 0
	v_permlane32_swap_b32_e32 v143, v145
	v_permlane32_swap_b32_e32 v142, v144
	v_pk_add_f32 v[138:139], v[142:143], v[144:145]
	v_mov_b32_e32 v142, v135
	v_mov_b32_e32 v143, v136
	v_mov_b32_e32 v135, v137
	v_pk_add_f32 v[134:135], v[142:143], v[134:135]
	v_mov_b32_e32 v142, v131
	v_mov_b32_e32 v143, v132
	v_mov_b32_e32 v131, v133
	v_pk_add_f32 v[130:131], v[142:143], v[130:131]
	v_pk_add_f32 v[134:135], v[134:135], v[134:135] op_sel:[0,1] op_sel_hi:[1,0]
	v_pk_add_f32 v[130:131], v[130:131], v[130:131] op_sel:[0,1] op_sel_hi:[1,0]
	v_mov_b32_e32 v135, v134
	v_mov_b32_e32 v131, v130
	s_nop 0
	v_permlane16_swap_b32_e32 v134, v135
	v_permlane16_swap_b32_e32 v130, v131
	v_pk_fma_f32 v[146:147], v[146:147], s[4:5], v[186:187] op_sel_hi:[1,0,0]
	v_add_f32_e32 v135, v134, v135
	v_add_f32_e32 v134, v130, v131
	v_mul_f32_e32 v148, 0x4b800000, v147
	v_cmp_gt_f32_e64 s[46:47], s50, v147
	v_mov_b32_e32 v137, v135
	v_mov_b32_e32 v136, v134
	v_rsq_f32_e32 v167, v167
	v_cndmask_b32_e64 v147, v147, v148, s[46:47]
	v_permlane32_swap_b32_e32 v135, v137
	v_permlane32_swap_b32_e32 v134, v136
; __device__ __forceinline__ unsigned cvtpk(float lo, float hi) { f32x2_t v = {lo, hi}; bf16x2_t b = __builtin_convertvector(v, bf16x2_t); return __builtin_bit_cast(unsigned, b); }
;     __device__ __forceinline__ void operator()(const AccT& acc, const Unit& u, int wr, int wc, int fr, int fq) const {
;     ...
;           for (int ai = 0; ai < 2; ++ai)
; #pragma unroll
;               for (int m = 0; m < 4; ++m) { const f32x4 a = pv[ai][m]; float t = (a[0] + a[1]) + (a[2] + a[3]); t = xsum_16_32(t); rsv[ai][m] = rsqrtf(t * (1.0f / DM) + EPS); } }
; #pragma unroll
;         for (int ai = 0; ai < 2; ++ai)
; #pragma unroll
;             for (int m = 0; m < 4; ++m) { const int row = row0 + ai * 128 + m * 16; const float rs = rsv[ai][m];
; #pragma unroll
;                 for (int bj = 0; bj < 2; ++bj) { float a[8];
; #pragma unroll
;                     for (int n = 0; n < 2; ++n)
; #pragma unroll
;                         for (int j = 0; j < 4; ++j) { const float x_ = acc[ai][bj][m][n][j]; a[n * 4 + j] = ACT ? __builtin_amdgcn_rcpf(1.0f + __builtin_amdgcn_exp2f(x_ * (-rs * LOG2E))) : x_ * rs; }
;                     u32x4 w; w.x = cvtpk(a[0], a[1]); w.y = cvtpk(a[2], a[3]); w.z = cvtpk(a[4], a[5]); w.w = cvtpk(a[6], a[7]);
;                     *(u32x4*)(O + (size_t)row * ldc + col0 + bj * 128) = w; } }
	v_rsq_f32_e32 v147, v147
	v_pk_add_f32 v[130:131], v[134:135], v[136:137]
	v_lshl_or_b32 v134, s14, 8, v188
	v_pk_mul_f32 v[126:127], v[126:127], v[184:185] op_sel_hi:[1,0]
	v_pk_mul_f32 v[128:129], v[128:129], v[184:185] op_sel_hi:[1,0]
	v_pk_mul_f32 v[122:123], v[122:123], v[184:185] op_sel_hi:[1,0]
	v_ashrrev_i32_e32 v135, 31, v134
	v_pk_mul_f32 v[124:125], v[124:125], v[184:185] op_sel_hi:[1,0]
	v_cvt_pk_bf16_f32 v126, v126, v127
	v_cvt_pk_bf16_f32 v127, v128, v129
	v_cvt_pk_bf16_f32 v128, v122, v123
	v_mov_b64_e32 v[122:123], s[70:71]
	v_cvt_pk_bf16_f32 v129, v124, v125
	v_mad_i64_i32 v[136:137], s[0:1], v180, s51, v[122:123]
	v_lshlrev_b64 v[124:125], 1, v[134:135]
	v_mul_f32_e32 v169, 0x45800000, v167
	v_lshl_add_u64 v[134:135], v[136:137], 0, v[124:125]
	v_cndmask_b32_e32 v182, v167, v169, vcc
	v_mul_f32_e32 v148, 0x45800000, v147
	global_store_dwordx4 v[134:135], v[126:129], off
	v_pk_mul_f32 v[118:119], v[118:119], v[184:185] op_sel_hi:[1,0]
	v_pk_mul_f32 v[120:121], v[120:121], v[184:185] op_sel_hi:[1,0]
	v_pk_mul_f32 v[126:127], v[114:115], v[184:185] op_sel_hi:[1,0]
	v_pk_mul_f32 v[128:129], v[116:117], v[184:185] op_sel_hi:[1,0]
	v_cmp_gt_f32_e32 vcc, s50, v146
	v_cndmask_b32_e64 v148, v147, v148, s[46:47]
	v_mul_f32_e32 v147, 0x4b800000, v146
	v_pk_fma_f32 v[138:139], v[138:139], s[4:5], v[186:187] op_sel_hi:[1,0,0]
	v_cvt_pk_bf16_f32 v114, v118, v119
	v_cvt_pk_bf16_f32 v115, v120, v121
	v_cvt_pk_bf16_f32 v116, v126, v127
	v_cvt_pk_bf16_f32 v117, v128, v129
	v_pk_mul_f32 v[110:111], v[110:111], v[182:183] op_sel_hi:[1,0]
	v_cndmask_b32_e32 v146, v146, v147, vcc
	v_mul_f32_e32 v140, 0x4b800000, v139
	v_cmp_gt_f32_e64 s[46:47], s50, v139
	global_store_dwordx4 v[134:135], v[114:117], off offset:256
	v_pk_mul_f32 v[112:113], v[112:113], v[182:183] op_sel_hi:[1,0]
	v_rsq_f32_e32 v146, v146
	v_pk_mul_f32 v[114:115], v[106:107], v[182:183] op_sel_hi:[1,0]
	v_pk_mul_f32 v[116:117], v[108:109], v[182:183] op_sel_hi:[1,0]
	v_cvt_pk_bf16_f32 v106, v110, v111
	v_mad_i64_i32 v[110:111], s[0:1], v178, s51, v[122:123]
	v_cndmask_b32_e64 v139, v139, v140, s[46:47]
	v_cvt_pk_bf16_f32 v107, v112, v113
	v_cvt_pk_bf16_f32 v108, v114, v115
	v_cvt_pk_bf16_f32 v109, v116, v117
	v_lshl_add_u64 v[110:111], v[110:111], 0, v[124:125]
	v_rsq_f32_e32 v139, v139
	global_store_dwordx4 v[110:111], v[106:109], off
	v_pk_mul_f32 v[102:103], v[102:103], v[182:183] op_sel_hi:[1,0]
	v_pk_mul_f32 v[104:105], v[104:105], v[182:183] op_sel_hi:[1,0]
	v_pk_mul_f32 v[106:107], v[98:99], v[182:183] op_sel_hi:[1,0]
	v_pk_mul_f32 v[108:109], v[100:101], v[182:183] op_sel_hi:[1,0]
	v_cvt_pk_bf16_f32 v98, v102, v103
	v_cvt_pk_bf16_f32 v99, v104, v105
	v_cvt_pk_bf16_f32 v100, v106, v107
	v_cvt_pk_bf16_f32 v101, v108, v109
	v_pk_mul_f32 v[94:95], v[94:95], v[148:149] op_sel_hi:[1,0]
	global_store_dwordx4 v[110:111], v[98:101], off offset:256
	v_pk_mul_f32 v[96:97], v[96:97], v[148:149] op_sel_hi:[1,0]
	v_mul_f32_e32 v147, 0x45800000, v146
	v_pk_mul_f32 v[98:99], v[90:91], v[148:149] op_sel_hi:[1,0]
	v_pk_mul_f32 v[100:101], v[92:93], v[148:149] op_sel_hi:[1,0]
	v_cvt_pk_bf16_f32 v90, v94, v95
	v_mad_i64_i32 v[94:95], s[0:1], v176, s51, v[122:123]
	v_cvt_pk_bf16_f32 v91, v96, v97
	v_cvt_pk_bf16_f32 v92, v98, v99
	v_cvt_pk_bf16_f32 v93, v100, v101
	v_lshl_add_u64 v[94:95], v[94:95], 0, v[124:125]
	v_cndmask_b32_e32 v146, v146, v147, vcc
	v_mul_f32_e32 v140, 0x45800000, v139
	global_store_dwordx4 v[94:95], v[90:93], off
	v_pk_mul_f32 v[86:87], v[86:87], v[148:149] op_sel_hi:[1,0]
	v_pk_mul_f32 v[88:89], v[88:89], v[148:149] op_sel_hi:[1,0]
	v_pk_mul_f32 v[90:91], v[82:83], v[148:149] op_sel_hi:[1,0]
	v_pk_mul_f32 v[92:93], v[84:85], v[148:149] op_sel_hi:[1,0]
	v_cmp_gt_f32_e32 vcc, s50, v138
	v_cndmask_b32_e64 v140, v139, v140, s[46:47]
	v_mul_f32_e32 v139, 0x4b800000, v138
	v_pk_fma_f32 v[130:131], v[130:131], s[4:5], v[186:187] op_sel_hi:[1,0,0]
	v_cvt_pk_bf16_f32 v82, v86, v87
	v_cvt_pk_bf16_f32 v83, v88, v89
	v_cvt_pk_bf16_f32 v84, v90, v91
	v_cvt_pk_bf16_f32 v85, v92, v93
	v_pk_mul_f32 v[78:79], v[78:79], v[146:147] op_sel_hi:[1,0]
	v_cndmask_b32_e32 v138, v138, v139, vcc
	v_mul_f32_e32 v132, 0x4b800000, v131
	v_cmp_gt_f32_e64 s[46:47], s50, v131
	global_store_dwordx4 v[94:95], v[82:85], off offset:256
	v_pk_mul_f32 v[80:81], v[80:81], v[146:147] op_sel_hi:[1,0]
	v_rsq_f32_e32 v138, v138
	v_pk_mul_f32 v[82:83], v[74:75], v[146:147] op_sel_hi:[1,0]
	v_pk_mul_f32 v[84:85], v[76:77], v[146:147] op_sel_hi:[1,0]
	v_cvt_pk_bf16_f32 v74, v78, v79
	v_mad_i64_i32 v[78:79], s[0:1], v174, s51, v[122:123]
	v_cndmask_b32_e64 v131, v131, v132, s[46:47]
	v_cvt_pk_bf16_f32 v75, v80, v81
	v_cvt_pk_bf16_f32 v76, v82, v83
	v_cvt_pk_bf16_f32 v77, v84, v85
	v_lshl_add_u64 v[78:79], v[78:79], 0, v[124:125]
	v_rsq_f32_e32 v131, v131
	global_store_dwordx4 v[78:79], v[74:77], off
; __device__ __forceinline__ unsigned cvtpk(float lo, float hi) { f32x2_t v = {lo, hi}; bf16x2_t b = __builtin_convertvector(v, bf16x2_t); return __builtin_bit_cast(unsigned, b); }
;     __device__ __forceinline__ void operator()(const AccT& acc, const Unit& u, int wr, int wc, int fr, int fq) const {
;     ...
;         for (int ai = 0; ai < 2; ++ai)
; #pragma unroll
;             for (int m = 0; m < 4; ++m) { const int row = row0 + ai * 128 + m * 16; const float rs = rsv[ai][m];
; #pragma unroll
;                 for (int bj = 0; bj < 2; ++bj) { float a[8];
; #pragma unroll
;                     for (int n = 0; n < 2; ++n)
; #pragma unroll
;                         for (int j = 0; j < 4; ++j) { const float x_ = acc[ai][bj][m][n][j]; a[n * 4 + j] = ACT ? __builtin_amdgcn_rcpf(1.0f + __builtin_amdgcn_exp2f(x_ * (-rs * LOG2E))) : x_ * rs; }
;                     u32x4 w; w.x = cvtpk(a[0], a[1]); w.y = cvtpk(a[2], a[3]); w.z = cvtpk(a[4], a[5]); w.w = cvtpk(a[6], a[7]);
;                     *(u32x4*)(O + (size_t)row * ldc + col0 + bj * 128) = w; } }
	v_pk_mul_f32 v[70:71], v[70:71], v[146:147] op_sel_hi:[1,0]
	v_pk_mul_f32 v[72:73], v[72:73], v[146:147] op_sel_hi:[1,0]
	v_pk_mul_f32 v[74:75], v[66:67], v[146:147] op_sel_hi:[1,0]
	v_pk_mul_f32 v[76:77], v[68:69], v[146:147] op_sel_hi:[1,0]
	v_cvt_pk_bf16_f32 v66, v70, v71
	v_cvt_pk_bf16_f32 v67, v72, v73
	v_cvt_pk_bf16_f32 v68, v74, v75
	v_cvt_pk_bf16_f32 v69, v76, v77
	v_pk_mul_f32 v[62:63], v[62:63], v[140:141] op_sel_hi:[1,0]
	global_store_dwordx4 v[78:79], v[66:69], off offset:256
	v_pk_mul_f32 v[64:65], v[64:65], v[140:141] op_sel_hi:[1,0]
	v_mul_f32_e32 v139, 0x45800000, v138
	v_pk_mul_f32 v[66:67], v[58:59], v[140:141] op_sel_hi:[1,0]
	v_pk_mul_f32 v[68:69], v[60:61], v[140:141] op_sel_hi:[1,0]
	v_cvt_pk_bf16_f32 v58, v62, v63
	v_mad_i64_i32 v[62:63], s[0:1], v172, s51, v[122:123]
	v_cvt_pk_bf16_f32 v59, v64, v65
	v_cvt_pk_bf16_f32 v60, v66, v67
	v_cvt_pk_bf16_f32 v61, v68, v69
	v_lshl_add_u64 v[62:63], v[62:63], 0, v[124:125]
	v_cndmask_b32_e32 v138, v138, v139, vcc
	v_mul_f32_e32 v132, 0x45800000, v131
	global_store_dwordx4 v[62:63], v[58:61], off
	v_pk_mul_f32 v[54:55], v[54:55], v[140:141] op_sel_hi:[1,0]
	v_pk_mul_f32 v[56:57], v[56:57], v[140:141] op_sel_hi:[1,0]
	v_pk_mul_f32 v[58:59], v[50:51], v[140:141] op_sel_hi:[1,0]
	v_pk_mul_f32 v[60:61], v[52:53], v[140:141] op_sel_hi:[1,0]
	v_cmp_gt_f32_e32 vcc, s50, v130
	v_cndmask_b32_e64 v132, v131, v132, s[46:47]
	v_mul_f32_e32 v131, 0x4b800000, v130
	v_cvt_pk_bf16_f32 v50, v54, v55
	v_cvt_pk_bf16_f32 v51, v56, v57
	v_cvt_pk_bf16_f32 v52, v58, v59
	v_cvt_pk_bf16_f32 v53, v60, v61
	v_pk_mul_f32 v[46:47], v[46:47], v[138:139] op_sel_hi:[1,0]
	v_cndmask_b32_e32 v130, v130, v131, vcc
	global_store_dwordx4 v[62:63], v[50:53], off offset:256
	v_pk_mul_f32 v[48:49], v[48:49], v[138:139] op_sel_hi:[1,0]
	v_rsq_f32_e32 v130, v130
	v_pk_mul_f32 v[50:51], v[42:43], v[138:139] op_sel_hi:[1,0]
	v_pk_mul_f32 v[52:53], v[44:45], v[138:139] op_sel_hi:[1,0]
	v_cvt_pk_bf16_f32 v42, v46, v47
	v_mad_i64_i32 v[46:47], s[0:1], v170, s51, v[122:123]
	v_cvt_pk_bf16_f32 v43, v48, v49
	v_cvt_pk_bf16_f32 v44, v50, v51
	v_cvt_pk_bf16_f32 v45, v52, v53
	v_lshl_add_u64 v[46:47], v[46:47], 0, v[124:125]
	global_store_dwordx4 v[46:47], v[42:45], off
	v_pk_mul_f32 v[38:39], v[38:39], v[138:139] op_sel_hi:[1,0]
	v_pk_mul_f32 v[40:41], v[40:41], v[138:139] op_sel_hi:[1,0]
	v_pk_mul_f32 v[42:43], v[34:35], v[138:139] op_sel_hi:[1,0]
	v_pk_mul_f32 v[44:45], v[36:37], v[138:139] op_sel_hi:[1,0]
	v_cvt_pk_bf16_f32 v34, v38, v39
	v_cvt_pk_bf16_f32 v35, v40, v41
	v_cvt_pk_bf16_f32 v36, v42, v43
	v_cvt_pk_bf16_f32 v37, v44, v45
	v_pk_mul_f32 v[30:31], v[30:31], v[132:133] op_sel_hi:[1,0]
	global_store_dwordx4 v[46:47], v[34:37], off offset:256
	v_pk_mul_f32 v[32:33], v[32:33], v[132:133] op_sel_hi:[1,0]
	v_mul_f32_e32 v131, 0x45800000, v130
	v_pk_mul_f32 v[34:35], v[26:27], v[132:133] op_sel_hi:[1,0]
	v_pk_mul_f32 v[36:37], v[28:29], v[132:133] op_sel_hi:[1,0]
	v_cvt_pk_bf16_f32 v26, v30, v31
	v_mad_i64_i32 v[30:31], s[0:1], v168, s51, v[122:123]
	v_cvt_pk_bf16_f32 v27, v32, v33
	v_cvt_pk_bf16_f32 v28, v34, v35
	v_cvt_pk_bf16_f32 v29, v36, v37
	v_lshl_add_u64 v[30:31], v[30:31], 0, v[124:125]
	v_cndmask_b32_e32 v130, v130, v131, vcc
	global_store_dwordx4 v[30:31], v[26:29], off
	v_pk_mul_f32 v[22:23], v[22:23], v[132:133] op_sel_hi:[1,0]
	v_pk_mul_f32 v[24:25], v[24:25], v[132:133] op_sel_hi:[1,0]
	v_pk_mul_f32 v[26:27], v[18:19], v[132:133] op_sel_hi:[1,0]
	v_pk_mul_f32 v[28:29], v[20:21], v[132:133] op_sel_hi:[1,0]
	v_cvt_pk_bf16_f32 v18, v22, v23
	v_cvt_pk_bf16_f32 v19, v24, v25
	v_cvt_pk_bf16_f32 v20, v26, v27
	v_cvt_pk_bf16_f32 v21, v28, v29
	v_pk_mul_f32 v[14:15], v[14:15], v[130:131] op_sel_hi:[1,0]
	global_store_dwordx4 v[30:31], v[18:21], off offset:256
	v_pk_mul_f32 v[16:17], v[16:17], v[130:131] op_sel_hi:[1,0]
	v_pk_mul_f32 v[6:7], v[6:7], v[130:131] op_sel_hi:[1,0]
	v_pk_mul_f32 v[18:19], v[10:11], v[130:131] op_sel_hi:[1,0]
	v_pk_mul_f32 v[20:21], v[12:13], v[130:131] op_sel_hi:[1,0]
	v_cvt_pk_bf16_f32 v10, v14, v15
	v_mad_i64_i32 v[14:15], s[0:1], v166, s51, v[122:123]
	v_cvt_pk_bf16_f32 v11, v16, v17
	v_cvt_pk_bf16_f32 v12, v18, v19
	v_cvt_pk_bf16_f32 v13, v20, v21
	v_lshl_add_u64 v[14:15], v[14:15], 0, v[124:125]
	global_store_dwordx4 v[14:15], v[10:13], off
	v_pk_mul_f32 v[8:9], v[8:9], v[130:131] op_sel_hi:[1,0]
	s_mov_b64 s[0:1], -1
	v_pk_mul_f32 v[10:11], v[2:3], v[130:131] op_sel_hi:[1,0]
	v_pk_mul_f32 v[12:13], v[4:5], v[130:131] op_sel_hi:[1,0]
	v_cvt_pk_bf16_f32 v2, v6, v7
	v_cvt_pk_bf16_f32 v3, v8, v9
	v_cvt_pk_bf16_f32 v4, v10, v11
	v_cvt_pk_bf16_f32 v5, v12, v13
	s_and_b64 vcc, exec, s[44:45]
	global_store_dwordx4 v[14:15], v[2:5], off offset:256
	s_cbranch_vccnz .LBB0_419
	s_andn2_b64 vcc, exec, s[58:59]
	s_cbranch_vccnz .LBB0_418
	s_barrier
	s_branch .LBB0_418

; #define PG8_BAR __builtin_amdgcn_s_barrier()
; template <class Epi, class Sched>
; __device__ __forceinline__ void gemm_phase(LAS unsigned char* lds, const Gemm g, const Sched& S, const Epi& E) {
;     ...
;         if (wr == 0) PG8_BAR;
;     __device__ __forceinline__ void operator()(const AccT& acc, const Unit& u, int wr, int wc, int fr, int fq) const {
;         const int row0 = u.pm * 256 + wr * 64 + fr, col0 = u.pn * 256 + wc * 32 + 8 * fq;
;         float rsv[2][4];
;         { f32x4 pv[2][4];
; #pragma unroll
;           for (int ai = 0; ai < 2; ++ai)
; #pragma unroll
;               for (int m = 0; m < 4; ++m) pv[ai][m] = *(const f32x4*)(ss + (size_t)(row0 + ai * 128 + m * 16) * 16 + fq * 4);
; #pragma unroll
;           for (int ai = 0; ai < 2; ++ai)
; #pragma unroll
;               for (int m = 0; m < 4; ++m) { const f32x4 a = pv[ai][m]; float t = (a[0] + a[1]) + (a[2] + a[3]); t = xsum_16_32(t); rsv[ai][m] = rsqrtf(t * (1.0f / DM) + EPS); } }
.LBB0_1441:
	v_lshl_add_u32 v180, s90, 8, v184
	v_ashrrev_i32_e32 v181, 31, v180
	v_lshlrev_b64 v[130:131], 6, v[180:181]
	v_or_b32_e32 v178, 16, v180
	v_lshl_add_u64 v[130:131], v[160:161], 0, v[130:131]
	v_ashrrev_i32_e32 v179, 31, v178
	global_load_dwordx4 v[188:191], v[130:131], off
	v_lshlrev_b64 v[130:131], 6, v[178:179]
	v_lshl_add_u64 v[130:131], v[160:161], 0, v[130:131]
	global_load_dwordx4 v[206:209], v[130:131], off
	v_or_b32_e32 v176, 32, v180
	v_ashrrev_i32_e32 v177, 31, v176
	v_lshlrev_b64 v[130:131], 6, v[176:177]
	v_or_b32_e32 v174, 48, v180
	v_lshl_add_u64 v[130:131], v[160:161], 0, v[130:131]
	v_ashrrev_i32_e32 v175, 31, v174
	global_load_dwordx4 v[150:153], v[130:131], off
	v_lshlrev_b64 v[130:131], 6, v[174:175]
	v_lshl_add_u64 v[130:131], v[160:161], 0, v[130:131]
	global_load_dwordx4 v[146:149], v[130:131], off
	v_add_u32_e32 v172, 0x80, v180
	v_ashrrev_i32_e32 v173, 31, v172
	v_lshlrev_b64 v[130:131], 6, v[172:173]
	v_add_u32_e32 v170, 0x90, v180
	v_lshl_add_u64 v[130:131], v[160:161], 0, v[130:131]
	v_ashrrev_i32_e32 v171, 31, v170
	global_load_dwordx4 v[142:145], v[130:131], off
	v_lshlrev_b64 v[130:131], 6, v[170:171]
	v_lshl_add_u64 v[130:131], v[160:161], 0, v[130:131]
	global_load_dwordx4 v[138:141], v[130:131], off
	v_add_u32_e32 v168, 0xa0, v180
	v_ashrrev_i32_e32 v169, 31, v168
	v_lshlrev_b64 v[130:131], 6, v[168:169]
	v_add_u32_e32 v166, 0xb0, v180
	v_lshl_add_u64 v[130:131], v[160:161], 0, v[130:131]
	v_ashrrev_i32_e32 v167, 31, v166
	global_load_dwordx4 v[134:137], v[130:131], off
	v_lshlrev_b64 v[130:131], 6, v[166:167]
	v_lshl_add_u64 v[130:131], v[160:161], 0, v[130:131]
	global_load_dwordx4 v[130:133], v[130:131], off
	s_and_b64 vcc, exec, s[66:67]
	s_cbranch_vccz .LBB0_1443
	s_barrier
.LBB0_1443:
	s_mov_b32 s0, 0x358637bd
	s_waitcnt vmcnt(0)
	v_mov_b32_e32 v182, v189
	v_mov_b32_e32 v183, v190
	v_mov_b32_e32 v189, v191
	v_pk_add_f32 v[182:183], v[182:183], v[188:189]
	v_mov_b32_e32 v190, v207
	v_pk_add_f32 v[182:183], v[182:183], v[182:183] op_sel:[0,1] op_sel_hi:[1,0]
	v_mov_b32_e32 v191, v208
	v_mov_b32_e32 v207, v209
	v_mov_b32_e32 v167, v182
	v_pk_add_f32 v[190:191], v[190:191], v[206:207]
	s_nop 0
	v_permlane16_swap_b32_e32 v182, v167
	v_pk_add_f32 v[190:191], v[190:191], v[190:191] op_sel:[0,1] op_sel_hi:[1,0]
	v_add_f32_e32 v183, v182, v167
	v_mov_b32_e32 v167, v190
	s_nop 1
	v_permlane16_swap_b32_e32 v190, v167
	v_add_f32_e32 v182, v190, v167
	v_mov_b32_e32 v189, v183
	v_mov_b32_e32 v188, v182
	s_nop 0
	v_permlane32_swap_b32_e32 v183, v189
	v_permlane32_swap_b32_e32 v182, v188
	v_pk_add_f32 v[188:189], v[182:183], v[188:189]
	v_mov_b64_e32 v[182:183], s[0:1]
	v_pk_fma_f32 v[188:189], v[188:189], s[4:5], v[182:183] op_sel_hi:[1,0,0]
	s_nop 0
	v_mul_f32_e32 v167, 0x4b800000, v189
	v_cmp_gt_f32_e64 s[46:47], s50, v189
	v_cmp_gt_f32_e32 vcc, s50, v188
	s_nop 0
	v_cndmask_b32_e64 v167, v189, v167, s[46:47]
	v_rsq_f32_e32 v167, v167
	v_mov_b32_e32 v189, v152
	v_mul_f32_e32 v169, 0x45800000, v167
	v_cndmask_b32_e64 v169, v167, v169, s[46:47]
	v_mul_f32_e32 v167, 0x4b800000, v188
	v_cndmask_b32_e32 v167, v188, v167, vcc
	v_mov_b32_e32 v188, v151
	v_mov_b32_e32 v151, v153
	v_pk_add_f32 v[150:151], v[188:189], v[150:151]
	v_mov_b32_e32 v188, v147
	v_mov_b32_e32 v189, v148
	v_mov_b32_e32 v147, v149
	v_pk_add_f32 v[146:147], v[188:189], v[146:147]
	v_pk_add_f32 v[150:151], v[150:151], v[150:151] op_sel:[0,1] op_sel_hi:[1,0]
	v_pk_add_f32 v[146:147], v[146:147], v[146:147] op_sel:[0,1] op_sel_hi:[1,0]
	v_mov_b32_e32 v151, v150
	v_mov_b32_e32 v147, v146
	s_nop 0
	v_permlane16_swap_b32_e32 v150, v151
	v_permlane16_swap_b32_e32 v146, v147
	v_add_f32_e32 v151, v150, v151
	v_add_f32_e32 v150, v146, v147
	v_mov_b32_e32 v153, v151
	v_mov_b32_e32 v152, v150
	s_nop 0
	v_permlane32_swap_b32_e32 v151, v153
	v_permlane32_swap_b32_e32 v150, v152
	v_pk_add_f32 v[146:147], v[150:151], v[152:153]
	v_rsq_f32_e32 v167, v167
	v_pk_fma_f32 v[146:147], v[146:147], s[4:5], v[182:183] op_sel_hi:[1,0,0]
	v_mov_b32_e32 v149, v144
	v_mul_f32_e32 v148, 0x4b800000, v147
	v_cmp_gt_f32_e64 s[46:47], s50, v147
	v_mul_f32_e32 v171, 0x45800000, v167
	v_cndmask_b32_e32 v167, v167, v171, vcc
	v_cndmask_b32_e64 v147, v147, v148, s[46:47]
	v_rsq_f32_e32 v147, v147
	v_cmp_gt_f32_e32 vcc, s50, v146
	v_mul_f32_e32 v148, 0x45800000, v147
	v_cndmask_b32_e64 v147, v147, v148, s[46:47]
	v_mul_f32_e32 v148, 0x4b800000, v146
	v_cndmask_b32_e32 v146, v146, v148, vcc
	v_rsq_f32_e32 v146, v146
	s_nop 0
	v_mul_f32_e32 v148, 0x45800000, v146
	v_cndmask_b32_e32 v146, v146, v148, vcc
	v_mov_b32_e32 v148, v143
	v_mov_b32_e32 v143, v145
	v_pk_add_f32 v[142:143], v[148:149], v[142:143]
	v_mov_b32_e32 v148, v139
	v_mov_b32_e32 v149, v140
	v_mov_b32_e32 v139, v141
	v_pk_add_f32 v[138:139], v[148:149], v[138:139]
	v_pk_add_f32 v[142:143], v[142:143], v[142:143] op_sel:[0,1] op_sel_hi:[1,0]
	v_pk_add_f32 v[138:139], v[138:139], v[138:139] op_sel:[0,1] op_sel_hi:[1,0]
	v_mov_b32_e32 v143, v142
	v_mov_b32_e32 v139, v138
	s_nop 0
	v_permlane16_swap_b32_e32 v142, v143
	v_permlane16_swap_b32_e32 v138, v139
	v_add_f32_e32 v143, v142, v143
	v_add_f32_e32 v142, v138, v139
	v_mov_b32_e32 v145, v143
	v_mov_b32_e32 v144, v142
	s_nop 0
	v_permlane32_swap_b32_e32 v143, v145
	v_permlane32_swap_b32_e32 v142, v144
	v_pk_add_f32 v[138:139], v[142:143], v[144:145]
	v_mov_b32_e32 v141, v136
	v_pk_fma_f32 v[138:139], v[138:139], s[4:5], v[182:183] op_sel_hi:[1,0,0]
	s_nop 0
	v_mul_f32_e32 v140, 0x4b800000, v139
	v_cmp_gt_f32_e64 s[46:47], s50, v139
	v_cmp_gt_f32_e32 vcc, s50, v138
	s_nop 0
	v_cndmask_b32_e64 v139, v139, v140, s[46:47]
	v_rsq_f32_e32 v139, v139
	s_nop 0
; __device__ __forceinline__ unsigned cvtpk(float lo, float hi) { f32x2_t v = {lo, hi}; bf16x2_t b = __builtin_convertvector(v, bf16x2_t); return __builtin_bit_cast(unsigned, b); }
;     __device__ __forceinline__ void operator()(const AccT& acc, const Unit& u, int wr, int wc, int fr, int fq) const {
;     ...
;           for (int ai = 0; ai < 2; ++ai)
; #pragma unroll
;               for (int m = 0; m < 4; ++m) { const f32x4 a = pv[ai][m]; float t = (a[0] + a[1]) + (a[2] + a[3]); t = xsum_16_32(t); rsv[ai][m] = rsqrtf(t * (1.0f / DM) + EPS); } }
; #pragma unroll
;         for (int ai = 0; ai < 2; ++ai)
; #pragma unroll
;             for (int m = 0; m < 4; ++m) { const int row = row0 + ai * 128 + m * 16; const float rs = rsv[ai][m];
; #pragma unroll
;                 for (int bj = 0; bj < 2; ++bj) { float a[8];
; #pragma unroll
;                     for (int n = 0; n < 2; ++n)
; #pragma unroll
;                         for (int j = 0; j < 4; ++j) { const float x_ = acc[ai][bj][m][n][j]; a[n * 4 + j] = ACT ? __builtin_amdgcn_rcpf(1.0f + __builtin_amdgcn_exp2f(x_ * (-rs * LOG2E))) : x_ * rs; }
;                     u32x4 w; w.x = cvtpk(a[0], a[1]); w.y = cvtpk(a[2], a[3]); w.z = cvtpk(a[4], a[5]); w.w = cvtpk(a[6], a[7]);
;                     *(u32x4*)(O + (size_t)row * ldc + col0 + bj * 128) = w; } }
	v_mul_f32_e32 v140, 0x45800000, v139
	v_cndmask_b32_e64 v139, v139, v140, s[46:47]
	v_mul_f32_e32 v140, 0x4b800000, v138
	v_cndmask_b32_e32 v138, v138, v140, vcc
	v_rsq_f32_e32 v138, v138
	s_nop 0
	v_mul_f32_e32 v140, 0x45800000, v138
	v_cndmask_b32_e32 v138, v138, v140, vcc
	v_mov_b32_e32 v140, v135
	v_mov_b32_e32 v135, v137
	v_pk_add_f32 v[134:135], v[140:141], v[134:135]
	v_mov_b32_e32 v140, v131
	v_mov_b32_e32 v141, v132
	v_mov_b32_e32 v131, v133
	v_pk_add_f32 v[130:131], v[140:141], v[130:131]
	v_pk_add_f32 v[134:135], v[134:135], v[134:135] op_sel:[0,1] op_sel_hi:[1,0]
	v_pk_add_f32 v[130:131], v[130:131], v[130:131] op_sel:[0,1] op_sel_hi:[1,0]
	v_mov_b32_e32 v135, v134
	v_mov_b32_e32 v131, v130
	s_nop 0
	v_permlane16_swap_b32_e32 v134, v135
	v_permlane16_swap_b32_e32 v130, v131
	v_add_f32_e32 v135, v134, v135
	v_add_f32_e32 v134, v130, v131
	v_mov_b32_e32 v137, v135
	v_mov_b32_e32 v136, v134
	s_nop 0
	v_permlane32_swap_b32_e32 v135, v137
	v_permlane32_swap_b32_e32 v134, v136
	v_pk_add_f32 v[130:131], v[134:135], v[136:137]
	v_mul_f32_e32 v136, 0xbfb8aa3b, v169
	v_pk_fma_f32 v[130:131], v[130:131], s[4:5], v[182:183] op_sel_hi:[1,0,0]
	v_mul_f32_e32 v126, v126, v136
	v_mul_f32_e32 v132, 0x4b800000, v131
	v_cmp_gt_f32_e64 s[46:47], s50, v131
	v_mul_f32_e32 v127, v127, v136
	v_mul_f32_e32 v128, v128, v136
	v_cndmask_b32_e64 v131, v131, v132, s[46:47]
	v_rsq_f32_e32 v131, v131
	v_mul_f32_e32 v129, v129, v136
	v_mul_f32_e32 v122, v122, v136
	v_mul_f32_e32 v123, v123, v136
	v_mul_f32_e32 v132, 0x45800000, v131
	v_exp_f32_e32 v126, v126
	v_exp_f32_e32 v127, v127
	v_exp_f32_e32 v128, v128
	v_exp_f32_e32 v129, v129
	v_exp_f32_e32 v122, v122
	v_exp_f32_e32 v123, v123
	v_mul_f32_e32 v124, v124, v136
	v_mul_f32_e32 v125, v125, v136
	v_cmp_gt_f32_e32 vcc, s50, v130
	v_cndmask_b32_e64 v131, v131, v132, s[46:47]
	v_mul_f32_e32 v132, 0x4b800000, v130
	v_exp_f32_e32 v124, v124
	v_exp_f32_e32 v125, v125
	v_cndmask_b32_e32 v130, v130, v132, vcc
	v_rsq_f32_e32 v130, v130
	v_add_f32_e32 v126, 1.0, v126
	v_add_f32_e32 v127, 1.0, v127
	v_add_f32_e32 v128, 1.0, v128
	v_add_f32_e32 v129, 1.0, v129
	v_add_f32_e32 v122, 1.0, v122
	v_add_f32_e32 v123, 1.0, v123
	v_rcp_f32_e32 v126, v126
	v_rcp_f32_e32 v127, v127
	v_rcp_f32_e32 v128, v128
	v_rcp_f32_e32 v129, v129
	v_rcp_f32_e32 v122, v122
	v_rcp_f32_e32 v123, v123
	v_add_f32_e32 v124, 1.0, v124
	v_add_f32_e32 v125, 1.0, v125
	v_rcp_f32_e32 v124, v124
	v_rcp_f32_e32 v125, v125
	v_mul_f32_e32 v114, v114, v136
	v_mul_f32_e32 v132, 0x45800000, v130
	v_exp_f32_e32 v114, v114
	v_cndmask_b32_e32 v130, v130, v132, vcc
	v_lshl_or_b32 v132, s14, 8, v186
	v_ashrrev_i32_e32 v133, 31, v132
	v_cvt_pk_bf16_f32 v126, v126, v127
	v_cvt_pk_bf16_f32 v127, v128, v129
	v_cvt_pk_bf16_f32 v128, v122, v123
	v_mov_b64_e32 v[122:123], s[70:71]
	v_cvt_pk_bf16_f32 v129, v124, v125
	v_mad_i64_i32 v[134:135], s[0:1], v180, s5, v[122:123]
	v_lshlrev_b64 v[124:125], 1, v[132:133]
	v_lshl_add_u64 v[132:133], v[134:135], 0, v[124:125]
	v_add_f32_e32 v114, 1.0, v114
	global_store_dwordx4 v[132:133], v[126:129], off
	v_mul_f32_e32 v118, v118, v136
	v_mul_f32_e32 v119, v119, v136
	v_rcp_f32_e32 v126, v114
	v_mul_f32_e32 v114, v115, v136
	v_exp_f32_e32 v114, v114
	v_mul_f32_e32 v120, v120, v136
	v_mul_f32_e32 v121, v121, v136
	v_exp_f32_e32 v118, v118
	v_add_f32_e32 v114, 1.0, v114
	v_rcp_f32_e32 v127, v114
	v_mul_f32_e32 v114, v116, v136
	v_exp_f32_e32 v114, v114
	v_exp_f32_e32 v119, v119
	v_exp_f32_e32 v120, v120
	v_exp_f32_e32 v121, v121
	v_add_f32_e32 v114, 1.0, v114
	v_rcp_f32_e32 v128, v114
	v_mul_f32_e32 v114, v117, v136
	v_exp_f32_e32 v114, v114
	v_add_f32_e32 v118, 1.0, v118
	v_add_f32_e32 v119, 1.0, v119
	v_add_f32_e32 v120, 1.0, v120
	v_add_f32_e32 v121, 1.0, v121
	v_add_f32_e32 v114, 1.0, v114
	v_rcp_f32_e32 v118, v118
	v_rcp_f32_e32 v119, v119
	v_rcp_f32_e32 v120, v120
	v_rcp_f32_e32 v121, v121
	v_rcp_f32_e32 v117, v114
	v_cvt_pk_bf16_f32 v114, v118, v119
	v_cvt_pk_bf16_f32 v116, v126, v127
	v_cvt_pk_bf16_f32 v115, v120, v121
	v_cvt_pk_bf16_f32 v117, v128, v117
	global_store_dwordx4 v[132:133], v[114:117], off offset:256
	s_and_b64 vcc, exec, s[44:45]
	s_nop 0
	v_mul_f32_e32 v114, 0xbfb8aa3b, v167
	v_mul_f32_e32 v106, v106, v114
	v_exp_f32_e32 v106, v106
	v_mul_f32_e32 v110, v110, v114
	v_mul_f32_e32 v111, v111, v114
	v_exp_f32_e32 v110, v110
	v_add_f32_e32 v106, 1.0, v106
	v_rcp_f32_e32 v115, v106
	v_mul_f32_e32 v106, v107, v114
	v_exp_f32_e32 v106, v106
	v_exp_f32_e32 v111, v111
	v_mul_f32_e32 v112, v112, v114
	v_mul_f32_e32 v113, v113, v114
	v_add_f32_e32 v106, 1.0, v106
	v_rcp_f32_e32 v116, v106
	v_mul_f32_e32 v106, v108, v114
	v_exp_f32_e32 v106, v106
	v_exp_f32_e32 v112, v112
	v_exp_f32_e32 v113, v113
	v_add_f32_e32 v110, 1.0, v110
	v_add_f32_e32 v106, 1.0, v106
	v_rcp_f32_e32 v117, v106
	v_mul_f32_e32 v106, v109, v114
	v_exp_f32_e32 v106, v106
	v_add_f32_e32 v111, 1.0, v111
	v_rcp_f32_e32 v110, v110
	v_rcp_f32_e32 v111, v111
	v_add_f32_e32 v112, 1.0, v112
	v_add_f32_e32 v113, 1.0, v113
	v_add_f32_e32 v106, 1.0, v106
	v_mul_f32_e32 v98, v98, v114
	v_rcp_f32_e32 v112, v112
	v_rcp_f32_e32 v113, v113
	v_rcp_f32_e32 v109, v106
	v_exp_f32_e32 v98, v98
	v_cvt_pk_bf16_f32 v106, v110, v111
	v_mad_i64_i32 v[110:111], s[0:1], v178, s5, v[122:123]
	v_cvt_pk_bf16_f32 v107, v112, v113
	v_cvt_pk_bf16_f32 v108, v115, v116
	v_cvt_pk_bf16_f32 v109, v117, v109
	v_lshl_add_u64 v[110:111], v[110:111], 0, v[124:125]
	v_add_f32_e32 v98, 1.0, v98
	global_store_dwordx4 v[110:111], v[106:109], off
	v_mul_f32_e32 v102, v102, v114
	v_mul_f32_e32 v103, v103, v114
	v_rcp_f32_e32 v106, v98
	v_mul_f32_e32 v98, v99, v114
	v_exp_f32_e32 v98, v98
; __device__ __forceinline__ unsigned cvtpk(float lo, float hi) { f32x2_t v = {lo, hi}; bf16x2_t b = __builtin_convertvector(v, bf16x2_t); return __builtin_bit_cast(unsigned, b); }
;     __device__ __forceinline__ void operator()(const AccT& acc, const Unit& u, int wr, int wc, int fr, int fq) const {
;     ...
;         for (int ai = 0; ai < 2; ++ai)
; #pragma unroll
;             for (int m = 0; m < 4; ++m) { const int row = row0 + ai * 128 + m * 16; const float rs = rsv[ai][m];
; #pragma unroll
;                 for (int bj = 0; bj < 2; ++bj) { float a[8];
; #pragma unroll
;                     for (int n = 0; n < 2; ++n)
; #pragma unroll
;                         for (int j = 0; j < 4; ++j) { const float x_ = acc[ai][bj][m][n][j]; a[n * 4 + j] = ACT ? __builtin_amdgcn_rcpf(1.0f + __builtin_amdgcn_exp2f(x_ * (-rs * LOG2E))) : x_ * rs; }
;                     u32x4 w; w.x = cvtpk(a[0], a[1]); w.y = cvtpk(a[2], a[3]); w.z = cvtpk(a[4], a[5]); w.w = cvtpk(a[6], a[7]);
;                     *(u32x4*)(O + (size_t)row * ldc + col0 + bj * 128) = w; } }
	v_mul_f32_e32 v104, v104, v114
	v_mul_f32_e32 v105, v105, v114
	v_exp_f32_e32 v102, v102
	v_add_f32_e32 v98, 1.0, v98
	v_rcp_f32_e32 v107, v98
	v_mul_f32_e32 v98, v100, v114
	v_exp_f32_e32 v98, v98
	v_exp_f32_e32 v103, v103
	v_exp_f32_e32 v104, v104
	v_exp_f32_e32 v105, v105
	v_add_f32_e32 v98, 1.0, v98
	v_rcp_f32_e32 v108, v98
	v_mul_f32_e32 v98, v101, v114
	v_exp_f32_e32 v98, v98
	v_add_f32_e32 v102, 1.0, v102
	v_add_f32_e32 v103, 1.0, v103
	v_add_f32_e32 v104, 1.0, v104
	v_add_f32_e32 v105, 1.0, v105
	v_add_f32_e32 v98, 1.0, v98
	v_rcp_f32_e32 v102, v102
	v_rcp_f32_e32 v103, v103
	v_rcp_f32_e32 v104, v104
	v_rcp_f32_e32 v105, v105
	v_rcp_f32_e32 v101, v98
	v_cvt_pk_bf16_f32 v98, v102, v103
	v_cvt_pk_bf16_f32 v100, v106, v107
	v_cvt_pk_bf16_f32 v99, v104, v105
	v_cvt_pk_bf16_f32 v101, v108, v101
	global_store_dwordx4 v[110:111], v[98:101], off offset:256
	s_nop 1
	v_mul_f32_e32 v98, 0xbfb8aa3b, v147
	v_mul_f32_e32 v90, v90, v98
	v_exp_f32_e32 v90, v90
	v_mul_f32_e32 v94, v94, v98
	v_mul_f32_e32 v95, v95, v98
	v_exp_f32_e32 v94, v94
	v_add_f32_e32 v90, 1.0, v90
	v_rcp_f32_e32 v99, v90
	v_mul_f32_e32 v90, v91, v98
	v_exp_f32_e32 v90, v90
	v_exp_f32_e32 v95, v95
	v_mul_f32_e32 v96, v96, v98
	v_mul_f32_e32 v97, v97, v98
	v_add_f32_e32 v90, 1.0, v90
	v_rcp_f32_e32 v100, v90
	v_mul_f32_e32 v90, v92, v98
	v_exp_f32_e32 v90, v90
	v_exp_f32_e32 v96, v96
	v_exp_f32_e32 v97, v97
	v_add_f32_e32 v94, 1.0, v94
	v_add_f32_e32 v90, 1.0, v90
	v_rcp_f32_e32 v101, v90
	v_mul_f32_e32 v90, v93, v98
	v_exp_f32_e32 v90, v90
	v_add_f32_e32 v95, 1.0, v95
	v_rcp_f32_e32 v94, v94
	v_rcp_f32_e32 v95, v95
	v_add_f32_e32 v96, 1.0, v96
	v_add_f32_e32 v97, 1.0, v97
	v_add_f32_e32 v90, 1.0, v90
	v_mul_f32_e32 v82, v82, v98
	v_rcp_f32_e32 v96, v96
	v_rcp_f32_e32 v97, v97
	v_rcp_f32_e32 v93, v90
	v_exp_f32_e32 v82, v82
	v_cvt_pk_bf16_f32 v90, v94, v95
	v_mad_i64_i32 v[94:95], s[0:1], v176, s5, v[122:123]
	v_cvt_pk_bf16_f32 v91, v96, v97
	v_cvt_pk_bf16_f32 v92, v99, v100
	v_cvt_pk_bf16_f32 v93, v101, v93
	v_lshl_add_u64 v[94:95], v[94:95], 0, v[124:125]
	v_add_f32_e32 v82, 1.0, v82
	global_store_dwordx4 v[94:95], v[90:93], off
	v_mul_f32_e32 v86, v86, v98
	v_mul_f32_e32 v87, v87, v98
	v_rcp_f32_e32 v90, v82
	v_mul_f32_e32 v82, v83, v98
	v_exp_f32_e32 v82, v82
	v_mul_f32_e32 v88, v88, v98
	v_mul_f32_e32 v89, v89, v98
	v_exp_f32_e32 v86, v86
	v_add_f32_e32 v82, 1.0, v82
	v_rcp_f32_e32 v91, v82
	v_mul_f32_e32 v82, v84, v98
	v_exp_f32_e32 v82, v82
	v_exp_f32_e32 v87, v87
	v_exp_f32_e32 v88, v88
	v_exp_f32_e32 v89, v89
	v_add_f32_e32 v82, 1.0, v82
	v_rcp_f32_e32 v92, v82
	v_mul_f32_e32 v82, v85, v98
	v_exp_f32_e32 v82, v82
	v_add_f32_e32 v86, 1.0, v86
	v_add_f32_e32 v87, 1.0, v87
	v_add_f32_e32 v88, 1.0, v88
	v_add_f32_e32 v89, 1.0, v89
	v_add_f32_e32 v82, 1.0, v82
	v_rcp_f32_e32 v86, v86
	v_rcp_f32_e32 v87, v87
	v_rcp_f32_e32 v88, v88
	v_rcp_f32_e32 v89, v89
	v_rcp_f32_e32 v85, v82
	v_cvt_pk_bf16_f32 v82, v86, v87
	v_cvt_pk_bf16_f32 v84, v90, v91
	v_cvt_pk_bf16_f32 v83, v88, v89
	v_cvt_pk_bf16_f32 v85, v92, v85
	global_store_dwordx4 v[94:95], v[82:85], off offset:256
	s_nop 1
	v_mul_f32_e32 v82, 0xbfb8aa3b, v146
	v_mul_f32_e32 v74, v74, v82
	v_exp_f32_e32 v74, v74
	v_mul_f32_e32 v78, v78, v82
	v_mul_f32_e32 v79, v79, v82
	v_exp_f32_e32 v78, v78
	v_add_f32_e32 v74, 1.0, v74
	v_rcp_f32_e32 v83, v74
	v_mul_f32_e32 v74, v75, v82
	v_exp_f32_e32 v74, v74
	v_exp_f32_e32 v79, v79
	v_mul_f32_e32 v80, v80, v82
	v_mul_f32_e32 v81, v81, v82
	v_add_f32_e32 v74, 1.0, v74
	v_rcp_f32_e32 v84, v74
	v_mul_f32_e32 v74, v76, v82
	v_exp_f32_e32 v74, v74
	v_exp_f32_e32 v80, v80
	v_exp_f32_e32 v81, v81
	v_add_f32_e32 v78, 1.0, v78
	v_add_f32_e32 v74, 1.0, v74
	v_rcp_f32_e32 v85, v74
	v_mul_f32_e32 v74, v77, v82
	v_exp_f32_e32 v74, v74
	v_add_f32_e32 v79, 1.0, v79
	v_rcp_f32_e32 v78, v78
	v_rcp_f32_e32 v79, v79
	v_add_f32_e32 v80, 1.0, v80
	v_add_f32_e32 v81, 1.0, v81
	v_add_f32_e32 v74, 1.0, v74
	v_mul_f32_e32 v66, v66, v82
	v_rcp_f32_e32 v80, v80
	v_rcp_f32_e32 v81, v81
	v_rcp_f32_e32 v77, v74
	v_exp_f32_e32 v66, v66
	v_cvt_pk_bf16_f32 v74, v78, v79
	v_mad_i64_i32 v[78:79], s[0:1], v174, s5, v[122:123]
	v_cvt_pk_bf16_f32 v75, v80, v81
	v_cvt_pk_bf16_f32 v76, v83, v84
	v_cvt_pk_bf16_f32 v77, v85, v77
	v_lshl_add_u64 v[78:79], v[78:79], 0, v[124:125]
	v_add_f32_e32 v66, 1.0, v66
	global_store_dwordx4 v[78:79], v[74:77], off
	v_mul_f32_e32 v70, v70, v82
	v_mul_f32_e32 v71, v71, v82
	v_rcp_f32_e32 v74, v66
	v_mul_f32_e32 v66, v67, v82
	v_exp_f32_e32 v66, v66
	v_mul_f32_e32 v72, v72, v82
	v_mul_f32_e32 v73, v73, v82
	v_exp_f32_e32 v70, v70
	v_add_f32_e32 v66, 1.0, v66
	v_rcp_f32_e32 v75, v66
	v_mul_f32_e32 v66, v68, v82
	v_exp_f32_e32 v66, v66
	v_exp_f32_e32 v71, v71
	v_exp_f32_e32 v72, v72
	v_exp_f32_e32 v73, v73
	v_add_f32_e32 v66, 1.0, v66
	v_rcp_f32_e32 v76, v66
	v_mul_f32_e32 v66, v69, v82
	v_exp_f32_e32 v66, v66
	v_add_f32_e32 v70, 1.0, v70
	v_add_f32_e32 v71, 1.0, v71
	v_add_f32_e32 v72, 1.0, v72
	v_add_f32_e32 v73, 1.0, v73
	v_add_f32_e32 v66, 1.0, v66
	v_rcp_f32_e32 v70, v70
	v_rcp_f32_e32 v71, v71
	v_rcp_f32_e32 v72, v72
	v_rcp_f32_e32 v73, v73
	v_rcp_f32_e32 v69, v66
	v_cvt_pk_bf16_f32 v66, v70, v71
	v_cvt_pk_bf16_f32 v68, v74, v75
	v_cvt_pk_bf16_f32 v67, v72, v73
	v_cvt_pk_bf16_f32 v69, v76, v69
	global_store_dwordx4 v[78:79], v[66:69], off offset:256
	s_nop 1
	v_mul_f32_e32 v66, 0xbfb8aa3b, v139
	v_mul_f32_e32 v58, v58, v66
	v_exp_f32_e32 v58, v58
	v_mul_f32_e32 v62, v62, v66
	v_mul_f32_e32 v63, v63, v66
	v_exp_f32_e32 v62, v62
	v_add_f32_e32 v58, 1.0, v58
	v_rcp_f32_e32 v67, v58
	v_mul_f32_e32 v58, v59, v66
	v_exp_f32_e32 v58, v58
	v_exp_f32_e32 v63, v63
	v_mul_f32_e32 v64, v64, v66
; __device__ __forceinline__ unsigned cvtpk(float lo, float hi) { f32x2_t v = {lo, hi}; bf16x2_t b = __builtin_convertvector(v, bf16x2_t); return __builtin_bit_cast(unsigned, b); }
;     __device__ __forceinline__ void operator()(const AccT& acc, const Unit& u, int wr, int wc, int fr, int fq) const {
;     ...
;         for (int ai = 0; ai < 2; ++ai)
; #pragma unroll
;             for (int m = 0; m < 4; ++m) { const int row = row0 + ai * 128 + m * 16; const float rs = rsv[ai][m];
; #pragma unroll
;                 for (int bj = 0; bj < 2; ++bj) { float a[8];
; #pragma unroll
;                     for (int n = 0; n < 2; ++n)
; #pragma unroll
;                         for (int j = 0; j < 4; ++j) { const float x_ = acc[ai][bj][m][n][j]; a[n * 4 + j] = ACT ? __builtin_amdgcn_rcpf(1.0f + __builtin_amdgcn_exp2f(x_ * (-rs * LOG2E))) : x_ * rs; }
;                     u32x4 w; w.x = cvtpk(a[0], a[1]); w.y = cvtpk(a[2], a[3]); w.z = cvtpk(a[4], a[5]); w.w = cvtpk(a[6], a[7]);
;                     *(u32x4*)(O + (size_t)row * ldc + col0 + bj * 128) = w; } }
	v_mul_f32_e32 v65, v65, v66
	v_add_f32_e32 v58, 1.0, v58
	v_rcp_f32_e32 v68, v58
	v_mul_f32_e32 v58, v60, v66
	v_exp_f32_e32 v58, v58
	v_exp_f32_e32 v64, v64
	v_exp_f32_e32 v65, v65
	v_add_f32_e32 v62, 1.0, v62
	v_add_f32_e32 v58, 1.0, v58
	v_rcp_f32_e32 v69, v58
	v_mul_f32_e32 v58, v61, v66
	v_exp_f32_e32 v58, v58
	v_add_f32_e32 v63, 1.0, v63
	v_rcp_f32_e32 v62, v62
	v_rcp_f32_e32 v63, v63
	v_add_f32_e32 v64, 1.0, v64
	v_add_f32_e32 v65, 1.0, v65
	v_add_f32_e32 v58, 1.0, v58
	v_mul_f32_e32 v50, v50, v66
	v_rcp_f32_e32 v64, v64
	v_rcp_f32_e32 v65, v65
	v_rcp_f32_e32 v61, v58
	v_exp_f32_e32 v50, v50
	v_cvt_pk_bf16_f32 v58, v62, v63
	v_mad_i64_i32 v[62:63], s[0:1], v172, s5, v[122:123]
	v_cvt_pk_bf16_f32 v59, v64, v65
	v_cvt_pk_bf16_f32 v60, v67, v68
	v_cvt_pk_bf16_f32 v61, v69, v61
	v_lshl_add_u64 v[62:63], v[62:63], 0, v[124:125]
	v_add_f32_e32 v50, 1.0, v50
	global_store_dwordx4 v[62:63], v[58:61], off
	v_mul_f32_e32 v54, v54, v66
	v_mul_f32_e32 v55, v55, v66
	v_rcp_f32_e32 v58, v50
	v_mul_f32_e32 v50, v51, v66
	v_exp_f32_e32 v50, v50
	v_mul_f32_e32 v56, v56, v66
	v_mul_f32_e32 v57, v57, v66
	v_exp_f32_e32 v54, v54
	v_add_f32_e32 v50, 1.0, v50
	v_rcp_f32_e32 v59, v50
	v_mul_f32_e32 v50, v52, v66
	v_exp_f32_e32 v50, v50
	v_exp_f32_e32 v55, v55
	v_exp_f32_e32 v56, v56
	v_exp_f32_e32 v57, v57
	v_add_f32_e32 v50, 1.0, v50
	v_rcp_f32_e32 v60, v50
	v_mul_f32_e32 v50, v53, v66
	v_exp_f32_e32 v50, v50
	v_add_f32_e32 v54, 1.0, v54
	v_add_f32_e32 v55, 1.0, v55
	v_add_f32_e32 v56, 1.0, v56
	v_add_f32_e32 v57, 1.0, v57
	v_add_f32_e32 v50, 1.0, v50
	v_rcp_f32_e32 v54, v54
	v_rcp_f32_e32 v55, v55
	v_rcp_f32_e32 v56, v56
	v_rcp_f32_e32 v57, v57
	v_rcp_f32_e32 v53, v50
	v_cvt_pk_bf16_f32 v50, v54, v55
	v_cvt_pk_bf16_f32 v52, v58, v59
	v_cvt_pk_bf16_f32 v51, v56, v57
	v_cvt_pk_bf16_f32 v53, v60, v53
	global_store_dwordx4 v[62:63], v[50:53], off offset:256
	s_nop 1
	v_mul_f32_e32 v50, 0xbfb8aa3b, v138
	v_mul_f32_e32 v42, v42, v50
	v_exp_f32_e32 v42, v42
	v_mul_f32_e32 v46, v46, v50
	v_mul_f32_e32 v47, v47, v50
	v_exp_f32_e32 v46, v46
	v_add_f32_e32 v42, 1.0, v42
	v_rcp_f32_e32 v51, v42
	v_mul_f32_e32 v42, v43, v50
	v_exp_f32_e32 v42, v42
	v_exp_f32_e32 v47, v47
	v_mul_f32_e32 v48, v48, v50
	v_mul_f32_e32 v49, v49, v50
	v_add_f32_e32 v42, 1.0, v42
	v_rcp_f32_e32 v52, v42
	v_mul_f32_e32 v42, v44, v50
	v_exp_f32_e32 v42, v42
	v_exp_f32_e32 v48, v48
	v_exp_f32_e32 v49, v49
	v_add_f32_e32 v46, 1.0, v46
	v_add_f32_e32 v42, 1.0, v42
	v_rcp_f32_e32 v53, v42
	v_mul_f32_e32 v42, v45, v50
	v_exp_f32_e32 v42, v42
	v_add_f32_e32 v47, 1.0, v47
	v_rcp_f32_e32 v46, v46
	v_rcp_f32_e32 v47, v47
	v_add_f32_e32 v48, 1.0, v48
	v_add_f32_e32 v49, 1.0, v49
	v_add_f32_e32 v42, 1.0, v42
	v_mul_f32_e32 v34, v34, v50
	v_rcp_f32_e32 v48, v48
	v_rcp_f32_e32 v49, v49
	v_rcp_f32_e32 v45, v42
	v_exp_f32_e32 v34, v34
	v_cvt_pk_bf16_f32 v42, v46, v47
	v_mad_i64_i32 v[46:47], s[0:1], v170, s5, v[122:123]
	v_cvt_pk_bf16_f32 v43, v48, v49
	v_cvt_pk_bf16_f32 v44, v51, v52
	v_cvt_pk_bf16_f32 v45, v53, v45
	v_lshl_add_u64 v[46:47], v[46:47], 0, v[124:125]
	v_add_f32_e32 v34, 1.0, v34
	global_store_dwordx4 v[46:47], v[42:45], off
	v_mul_f32_e32 v38, v38, v50
	v_mul_f32_e32 v39, v39, v50
	v_rcp_f32_e32 v42, v34
	v_mul_f32_e32 v34, v35, v50
	v_exp_f32_e32 v34, v34
	v_mul_f32_e32 v40, v40, v50
	v_mul_f32_e32 v41, v41, v50
	v_exp_f32_e32 v38, v38
	v_add_f32_e32 v34, 1.0, v34
	v_rcp_f32_e32 v43, v34
	v_mul_f32_e32 v34, v36, v50
	v_exp_f32_e32 v34, v34
	v_exp_f32_e32 v39, v39
	v_exp_f32_e32 v40, v40
	v_exp_f32_e32 v41, v41
	v_add_f32_e32 v34, 1.0, v34
	v_rcp_f32_e32 v44, v34
	v_mul_f32_e32 v34, v37, v50
	v_exp_f32_e32 v34, v34
	v_add_f32_e32 v38, 1.0, v38
	v_add_f32_e32 v39, 1.0, v39
	v_add_f32_e32 v40, 1.0, v40
	v_add_f32_e32 v41, 1.0, v41
	v_add_f32_e32 v34, 1.0, v34
	v_rcp_f32_e32 v38, v38
	v_rcp_f32_e32 v39, v39
	v_rcp_f32_e32 v40, v40
	v_rcp_f32_e32 v41, v41
	v_rcp_f32_e32 v37, v34
	v_cvt_pk_bf16_f32 v34, v38, v39
	v_cvt_pk_bf16_f32 v36, v42, v43
	v_cvt_pk_bf16_f32 v35, v40, v41
	v_cvt_pk_bf16_f32 v37, v44, v37
	global_store_dwordx4 v[46:47], v[34:37], off offset:256
	s_nop 1
	v_mul_f32_e32 v34, 0xbfb8aa3b, v131
	v_mul_f32_e32 v26, v26, v34
	v_exp_f32_e32 v26, v26
	v_mul_f32_e32 v30, v30, v34
	v_mul_f32_e32 v31, v31, v34
	v_exp_f32_e32 v30, v30
	v_add_f32_e32 v26, 1.0, v26
; __device__ __forceinline__ unsigned cvtpk(float lo, float hi) { f32x2_t v = {lo, hi}; bf16x2_t b = __builtin_convertvector(v, bf16x2_t); return __builtin_bit_cast(unsigned, b); }
;     __device__ __forceinline__ void operator()(const AccT& acc, const Unit& u, int wr, int wc, int fr, int fq) const {
;     ...
;         for (int ai = 0; ai < 2; ++ai)
; #pragma unroll
;             for (int m = 0; m < 4; ++m) { const int row = row0 + ai * 128 + m * 16; const float rs = rsv[ai][m];
; #pragma unroll
;                 for (int bj = 0; bj < 2; ++bj) { float a[8];
; #pragma unroll
;                     for (int n = 0; n < 2; ++n)
; #pragma unroll
;                         for (int j = 0; j < 4; ++j) { const float x_ = acc[ai][bj][m][n][j]; a[n * 4 + j] = ACT ? __builtin_amdgcn_rcpf(1.0f + __builtin_amdgcn_exp2f(x_ * (-rs * LOG2E))) : x_ * rs; }
;                     u32x4 w; w.x = cvtpk(a[0], a[1]); w.y = cvtpk(a[2], a[3]); w.z = cvtpk(a[4], a[5]); w.w = cvtpk(a[6], a[7]);
;                     *(u32x4*)(O + (size_t)row * ldc + col0 + bj * 128) = w; } }
	v_rcp_f32_e32 v35, v26
	v_mul_f32_e32 v26, v27, v34
	v_exp_f32_e32 v26, v26
	v_exp_f32_e32 v31, v31
	v_mul_f32_e32 v32, v32, v34
	v_mul_f32_e32 v33, v33, v34
	v_add_f32_e32 v26, 1.0, v26
	v_rcp_f32_e32 v36, v26
	v_mul_f32_e32 v26, v28, v34
	v_exp_f32_e32 v26, v26
	v_exp_f32_e32 v32, v32
	v_exp_f32_e32 v33, v33
	v_add_f32_e32 v30, 1.0, v30
	v_add_f32_e32 v26, 1.0, v26
	v_rcp_f32_e32 v37, v26
	v_mul_f32_e32 v26, v29, v34
	v_exp_f32_e32 v26, v26
	v_add_f32_e32 v31, 1.0, v31
	v_rcp_f32_e32 v30, v30
	v_rcp_f32_e32 v31, v31
	v_add_f32_e32 v32, 1.0, v32
	v_add_f32_e32 v33, 1.0, v33
	v_add_f32_e32 v26, 1.0, v26
	v_mul_f32_e32 v18, v18, v34
	v_rcp_f32_e32 v32, v32
	v_rcp_f32_e32 v33, v33
	v_rcp_f32_e32 v29, v26
	v_exp_f32_e32 v18, v18
	v_cvt_pk_bf16_f32 v26, v30, v31
	v_mad_i64_i32 v[30:31], s[0:1], v168, s5, v[122:123]
	v_cvt_pk_bf16_f32 v27, v32, v33
	v_cvt_pk_bf16_f32 v28, v35, v36
	v_cvt_pk_bf16_f32 v29, v37, v29
	v_lshl_add_u64 v[30:31], v[30:31], 0, v[124:125]
	v_add_f32_e32 v18, 1.0, v18
	global_store_dwordx4 v[30:31], v[26:29], off
	v_mul_f32_e32 v22, v22, v34
	v_mul_f32_e32 v23, v23, v34
	v_rcp_f32_e32 v26, v18
	v_mul_f32_e32 v18, v19, v34
	v_exp_f32_e32 v18, v18
	v_mul_f32_e32 v24, v24, v34
	v_mul_f32_e32 v25, v25, v34
	v_exp_f32_e32 v22, v22
	v_add_f32_e32 v18, 1.0, v18
	v_rcp_f32_e32 v27, v18
	v_mul_f32_e32 v18, v20, v34
	v_exp_f32_e32 v18, v18
	v_exp_f32_e32 v23, v23
	v_exp_f32_e32 v24, v24
	v_exp_f32_e32 v25, v25
	v_add_f32_e32 v18, 1.0, v18
	v_rcp_f32_e32 v28, v18
	v_mul_f32_e32 v18, v21, v34
	v_exp_f32_e32 v18, v18
	v_add_f32_e32 v22, 1.0, v22
	v_add_f32_e32 v23, 1.0, v23
	v_add_f32_e32 v24, 1.0, v24
	v_add_f32_e32 v25, 1.0, v25
	v_add_f32_e32 v18, 1.0, v18
	v_rcp_f32_e32 v22, v22
	v_rcp_f32_e32 v23, v23
	v_rcp_f32_e32 v24, v24
	v_rcp_f32_e32 v25, v25
	v_rcp_f32_e32 v21, v18
	v_cvt_pk_bf16_f32 v18, v22, v23
	v_cvt_pk_bf16_f32 v20, v26, v27
	v_cvt_pk_bf16_f32 v19, v24, v25
	v_cvt_pk_bf16_f32 v21, v28, v21
	global_store_dwordx4 v[30:31], v[18:21], off offset:256
	s_nop 1
	v_mul_f32_e32 v18, 0xbfb8aa3b, v130
	v_mul_f32_e32 v10, v10, v18
	v_exp_f32_e32 v10, v10
	v_mul_f32_e32 v14, v14, v18
	v_mul_f32_e32 v15, v15, v18
	v_exp_f32_e32 v14, v14
	v_add_f32_e32 v10, 1.0, v10
	v_rcp_f32_e32 v19, v10
	v_mul_f32_e32 v10, v11, v18
	v_exp_f32_e32 v10, v10
	v_exp_f32_e32 v15, v15
	v_mul_f32_e32 v16, v16, v18
	v_mul_f32_e32 v17, v17, v18
	v_add_f32_e32 v10, 1.0, v10
	v_rcp_f32_e32 v20, v10
	v_mul_f32_e32 v10, v12, v18
	v_exp_f32_e32 v10, v10
	v_exp_f32_e32 v16, v16
	v_exp_f32_e32 v17, v17
	v_add_f32_e32 v14, 1.0, v14
	v_add_f32_e32 v10, 1.0, v10
	v_rcp_f32_e32 v21, v10
	v_mul_f32_e32 v10, v13, v18
	v_exp_f32_e32 v10, v10
	v_add_f32_e32 v15, 1.0, v15
	v_rcp_f32_e32 v14, v14
	v_rcp_f32_e32 v15, v15
	v_add_f32_e32 v16, 1.0, v16
	v_add_f32_e32 v17, 1.0, v17
	v_add_f32_e32 v10, 1.0, v10
	v_mul_f32_e32 v2, v2, v18
	v_rcp_f32_e32 v16, v16
	v_rcp_f32_e32 v17, v17
	v_rcp_f32_e32 v13, v10
	v_exp_f32_e32 v2, v2
	v_cvt_pk_bf16_f32 v10, v14, v15
	v_mad_i64_i32 v[14:15], s[0:1], v166, s5, v[122:123]
	v_cvt_pk_bf16_f32 v11, v16, v17
	v_cvt_pk_bf16_f32 v12, v19, v20
	v_cvt_pk_bf16_f32 v13, v21, v13
	v_lshl_add_u64 v[14:15], v[14:15], 0, v[124:125]
	v_add_f32_e32 v2, 1.0, v2
	global_store_dwordx4 v[14:15], v[10:13], off
	v_mul_f32_e32 v6, v6, v18
	v_mul_f32_e32 v7, v7, v18
	v_rcp_f32_e32 v10, v2
	v_mul_f32_e32 v2, v3, v18
	v_exp_f32_e32 v2, v2
	v_mul_f32_e32 v8, v8, v18
	v_mul_f32_e32 v9, v9, v18
	v_exp_f32_e32 v6, v6
	v_add_f32_e32 v2, 1.0, v2
	v_rcp_f32_e32 v11, v2
	v_mul_f32_e32 v2, v4, v18
	v_exp_f32_e32 v2, v2
	v_exp_f32_e32 v7, v7
	v_exp_f32_e32 v8, v8
	v_exp_f32_e32 v9, v9
	v_add_f32_e32 v2, 1.0, v2
	v_rcp_f32_e32 v12, v2
	v_mul_f32_e32 v2, v5, v18
	v_exp_f32_e32 v2, v2
	v_add_f32_e32 v6, 1.0, v6
	v_add_f32_e32 v7, 1.0, v7
	v_add_f32_e32 v8, 1.0, v8
	v_add_f32_e32 v9, 1.0, v9
	v_add_f32_e32 v2, 1.0, v2
	v_rcp_f32_e32 v6, v6
	v_rcp_f32_e32 v7, v7
	v_rcp_f32_e32 v8, v8
	v_rcp_f32_e32 v9, v9
	v_rcp_f32_e32 v5, v2
	v_cvt_pk_bf16_f32 v2, v6, v7
	v_cvt_pk_bf16_f32 v4, v10, v11
	v_cvt_pk_bf16_f32 v3, v8, v9
	v_cvt_pk_bf16_f32 v5, v12, v5
	s_mov_b64 s[0:1], -1
	global_store_dwordx4 v[14:15], v[2:5], off offset:256
	s_cbranch_vccnz .LBB0_1431
	s_andn2_b64 vcc, exec, s[62:63]
	s_cbranch_vccnz .LBB0_1430
	s_barrier
	s_branch .LBB0_1430

; #define PG8_BAR __builtin_amdgcn_s_barrier()
; template <class Epi, class Sched>
; __device__ __forceinline__ void gemm_phase(LAS unsigned char* lds, const Gemm g, const Sched& S, const Epi& E) {
;     ...
;         if (wr == 0) PG8_BAR;
;     __device__ __forceinline__ void operator()(const AccT& acc, const Unit& u, int wr, int wc, int fr, int fq) const {
;         const int row0 = u.pm * 256 + wr * 64 + fr, col0 = u.pn * 128 + wc * 32 + 8 * fq;
;         float rsv[2][4];
;         { f32x4 pv[2][4];
; #pragma unroll
;           for (int ai = 0; ai < 2; ++ai)
; #pragma unroll
;               for (int m = 0; m < 4; ++m) pv[ai][m] = *(const f32x4*)(ss + (size_t)(row0 + ai * 128 + m * 16) * 16 + fq * 4);
; #pragma unroll
;           for (int ai = 0; ai < 2; ++ai)
; #pragma unroll
;               for (int m = 0; m < 4; ++m) { const f32x4 a = pv[ai][m]; float t = (a[0] + a[1]) + (a[2] + a[3]); t = xsum_16_32(t); rsv[ai][m] = rsqrtf(t * (1.0f / DM) + EPS); } }
; #pragma unroll
;         for (int ai = 0; ai < 2; ++ai)
; #pragma unroll
;             for (int m = 0; m < 4; ++m) { const int row = row0 + ai * 128 + m * 16; const float rs = rsv[ai][m]; const float c1 = -rs * LOG2E, c2 = rs * rs;
;                 float a[8];
; #pragma unroll
;                 for (int n = 0; n < 2; ++n)
; #pragma unroll
;                     for (int j = 0; j < 4; ++j) { const float g_ = acc[ai][0][m][n][j]; a[n * 4 + j] = (g_ * acc[ai][1][m][n][j]) * (c2 * __builtin_amdgcn_rcpf(1.0f + __builtin_amdgcn_exp2f(g_ * c1))); }
.LBB0_1909:
	v_lshl_add_u32 v180, s90, 8, v184
	v_ashrrev_i32_e32 v181, 31, v180
	v_lshlrev_b64 v[130:131], 6, v[180:181]
	v_or_b32_e32 v178, 16, v180
	v_lshl_add_u64 v[130:131], v[160:161], 0, v[130:131]
	v_ashrrev_i32_e32 v179, 31, v178
	global_load_dwordx4 v[188:191], v[130:131], off
	v_lshlrev_b64 v[130:131], 6, v[178:179]
	v_lshl_add_u64 v[130:131], v[160:161], 0, v[130:131]
	global_load_dwordx4 v[206:209], v[130:131], off
	v_or_b32_e32 v176, 32, v180
	v_ashrrev_i32_e32 v177, 31, v176
	v_lshlrev_b64 v[130:131], 6, v[176:177]
	v_or_b32_e32 v174, 48, v180
	v_lshl_add_u64 v[130:131], v[160:161], 0, v[130:131]
	v_ashrrev_i32_e32 v175, 31, v174
	global_load_dwordx4 v[150:153], v[130:131], off
	v_lshlrev_b64 v[130:131], 6, v[174:175]
	v_lshl_add_u64 v[130:131], v[160:161], 0, v[130:131]
	global_load_dwordx4 v[146:149], v[130:131], off
	v_add_u32_e32 v172, 0x80, v180
	v_ashrrev_i32_e32 v173, 31, v172
	v_lshlrev_b64 v[130:131], 6, v[172:173]
	v_add_u32_e32 v170, 0x90, v180
	v_lshl_add_u64 v[130:131], v[160:161], 0, v[130:131]
	v_ashrrev_i32_e32 v171, 31, v170
	global_load_dwordx4 v[142:145], v[130:131], off
	v_lshlrev_b64 v[130:131], 6, v[170:171]
	v_lshl_add_u64 v[130:131], v[160:161], 0, v[130:131]
	global_load_dwordx4 v[138:141], v[130:131], off
	v_add_u32_e32 v168, 0xa0, v180
	v_ashrrev_i32_e32 v169, 31, v168
	v_lshlrev_b64 v[130:131], 6, v[168:169]
	v_add_u32_e32 v166, 0xb0, v180
	v_lshl_add_u64 v[130:131], v[160:161], 0, v[130:131]
	v_ashrrev_i32_e32 v167, 31, v166
	global_load_dwordx4 v[134:137], v[130:131], off
	v_lshlrev_b64 v[130:131], 6, v[166:167]
	v_lshl_add_u64 v[130:131], v[160:161], 0, v[130:131]
	global_load_dwordx4 v[130:133], v[130:131], off
	s_and_b64 vcc, exec, s[62:63]
	s_cbranch_vccz .LBB0_1911
	s_barrier
.LBB0_1911:
	s_mov_b32 s0, 0x358637bd
	v_pk_mul_f32 v[120:121], v[120:121], v[116:117]
	v_pk_mul_f32 v[128:129], v[128:129], v[124:125]
	v_pk_mul_f32 v[112:113], v[112:113], v[108:109]
	v_pk_mul_f32 v[104:105], v[104:105], v[100:101]
	v_pk_mul_f32 v[96:97], v[96:97], v[92:93]
	v_pk_mul_f32 v[88:89], v[88:89], v[84:85]
	v_pk_mul_f32 v[80:81], v[80:81], v[76:77]
	v_pk_mul_f32 v[72:73], v[72:73], v[68:69]
	v_pk_mul_f32 v[64:65], v[64:65], v[60:61]
	v_pk_mul_f32 v[56:57], v[56:57], v[52:53]
	v_pk_mul_f32 v[48:49], v[48:49], v[44:45]
	v_pk_mul_f32 v[40:41], v[40:41], v[36:37]
	v_pk_mul_f32 v[32:33], v[32:33], v[28:29]
	v_pk_mul_f32 v[24:25], v[24:25], v[20:21]
	v_pk_mul_f32 v[16:17], v[16:17], v[12:13]
	v_pk_mul_f32 v[8:9], v[8:9], v[4:5]
	s_waitcnt vmcnt(0)
	v_mov_b32_e32 v182, v189
	v_mov_b32_e32 v183, v190
	v_mov_b32_e32 v189, v191
	v_pk_add_f32 v[182:183], v[182:183], v[188:189]
	v_mov_b32_e32 v190, v207
	v_pk_add_f32 v[182:183], v[182:183], v[182:183] op_sel:[0,1] op_sel_hi:[1,0]
	v_mov_b32_e32 v191, v208
	v_mov_b32_e32 v207, v209
	v_mov_b32_e32 v167, v182
	v_pk_add_f32 v[190:191], v[190:191], v[206:207]
	s_nop 0
	v_permlane16_swap_b32_e32 v182, v167
	v_pk_add_f32 v[190:191], v[190:191], v[190:191] op_sel:[0,1] op_sel_hi:[1,0]
	v_add_f32_e32 v183, v182, v167
	v_mov_b32_e32 v167, v190
	s_nop 1
	v_permlane16_swap_b32_e32 v190, v167
	v_add_f32_e32 v182, v190, v167
	v_mov_b32_e32 v189, v183
	v_mov_b32_e32 v188, v182
	s_nop 0
	v_permlane32_swap_b32_e32 v183, v189
	v_permlane32_swap_b32_e32 v182, v188
	v_pk_add_f32 v[188:189], v[182:183], v[188:189]
	v_mov_b64_e32 v[182:183], s[0:1]
	v_pk_fma_f32 v[188:189], v[188:189], s[4:5], v[182:183] op_sel_hi:[1,0,0]
	s_nop 0
	v_mul_f32_e32 v167, 0x4b800000, v189
	v_cmp_gt_f32_e64 s[44:45], s50, v189
	v_cmp_gt_f32_e32 vcc, s50, v188
	s_nop 0
	v_cndmask_b32_e64 v167, v189, v167, s[44:45]
	v_rsq_f32_e32 v167, v167
	v_mov_b32_e32 v189, v152
	v_mul_f32_e32 v169, 0x45800000, v167
	v_cndmask_b32_e64 v169, v167, v169, s[44:45]
	v_mul_f32_e32 v167, 0x4b800000, v188
	v_cndmask_b32_e32 v167, v188, v167, vcc
	v_mov_b32_e32 v188, v151
	v_mov_b32_e32 v151, v153
	v_pk_add_f32 v[150:151], v[188:189], v[150:151]
	v_mov_b32_e32 v188, v147
	v_mov_b32_e32 v189, v148
	v_mov_b32_e32 v147, v149
	v_pk_add_f32 v[146:147], v[188:189], v[146:147]
	v_pk_add_f32 v[150:151], v[150:151], v[150:151] op_sel:[0,1] op_sel_hi:[1,0]
	v_pk_add_f32 v[146:147], v[146:147], v[146:147] op_sel:[0,1] op_sel_hi:[1,0]
	v_mov_b32_e32 v151, v150
	v_mov_b32_e32 v147, v146
	s_nop 0
	v_permlane16_swap_b32_e32 v150, v151
	v_permlane16_swap_b32_e32 v146, v147
	v_add_f32_e32 v151, v150, v151
	v_add_f32_e32 v150, v146, v147
	v_mov_b32_e32 v153, v151
	v_mov_b32_e32 v152, v150
	s_nop 0
	v_permlane32_swap_b32_e32 v151, v153
	v_permlane32_swap_b32_e32 v150, v152
	v_pk_add_f32 v[146:147], v[150:151], v[152:153]
	v_rsq_f32_e32 v167, v167
	v_pk_fma_f32 v[146:147], v[146:147], s[4:5], v[182:183] op_sel_hi:[1,0,0]
	v_mov_b32_e32 v149, v144
	v_mul_f32_e32 v148, 0x4b800000, v147
	v_cmp_gt_f32_e64 s[44:45], s50, v147
	v_mul_f32_e32 v171, 0x45800000, v167
	v_cndmask_b32_e32 v167, v167, v171, vcc
	v_cndmask_b32_e64 v147, v147, v148, s[44:45]
	v_rsq_f32_e32 v147, v147
	v_cmp_gt_f32_e32 vcc, s50, v146
	v_mul_f32_e32 v148, 0x45800000, v147
	v_cndmask_b32_e64 v147, v147, v148, s[44:45]
	v_mul_f32_e32 v148, 0x4b800000, v146
	v_cndmask_b32_e32 v146, v146, v148, vcc
	v_rsq_f32_e32 v146, v146
	s_nop 0
	v_mul_f32_e32 v148, 0x45800000, v146
	v_cndmask_b32_e32 v146, v146, v148, vcc
	v_mov_b32_e32 v148, v143
	v_mov_b32_e32 v143, v145
	v_pk_add_f32 v[142:143], v[148:149], v[142:143]
	v_mov_b32_e32 v148, v139
	v_mov_b32_e32 v149, v140
	v_mov_b32_e32 v139, v141
	v_pk_add_f32 v[138:139], v[148:149], v[138:139]
	v_pk_add_f32 v[142:143], v[142:143], v[142:143] op_sel:[0,1] op_sel_hi:[1,0]
	v_pk_add_f32 v[138:139], v[138:139], v[138:139] op_sel:[0,1] op_sel_hi:[1,0]
; __device__ __forceinline__ unsigned cvtpk(float lo, float hi) { f32x2_t v = {lo, hi}; bf16x2_t b = __builtin_convertvector(v, bf16x2_t); return __builtin_bit_cast(unsigned, b); }
;     __device__ __forceinline__ void operator()(const AccT& acc, const Unit& u, int wr, int wc, int fr, int fq) const {
;     ...
;               for (int m = 0; m < 4; ++m) { const f32x4 a = pv[ai][m]; float t = (a[0] + a[1]) + (a[2] + a[3]); t = xsum_16_32(t); rsv[ai][m] = rsqrtf(t * (1.0f / DM) + EPS); } }
; #pragma unroll
;         for (int ai = 0; ai < 2; ++ai)
; #pragma unroll
;             for (int m = 0; m < 4; ++m) { const int row = row0 + ai * 128 + m * 16; const float rs = rsv[ai][m]; const float c1 = -rs * LOG2E, c2 = rs * rs;
;                 float a[8];
; #pragma unroll
;                 for (int n = 0; n < 2; ++n)
; #pragma unroll
;                     for (int j = 0; j < 4; ++j) { const float g_ = acc[ai][0][m][n][j]; a[n * 4 + j] = (g_ * acc[ai][1][m][n][j]) * (c2 * __builtin_amdgcn_rcpf(1.0f + __builtin_amdgcn_exp2f(g_ * c1))); }
;                 u32x4 w; w.x = cvtpk(a[0], a[1]); w.y = cvtpk(a[2], a[3]); w.z = cvtpk(a[4], a[5]); w.w = cvtpk(a[6], a[7]);
;                 *(u32x4*)(O + (size_t)row * DFF + col0) = w; }
	v_mov_b32_e32 v143, v142
	v_mov_b32_e32 v139, v138
	s_nop 0
	v_permlane16_swap_b32_e32 v142, v143
	v_permlane16_swap_b32_e32 v138, v139
	v_add_f32_e32 v143, v142, v143
	v_add_f32_e32 v142, v138, v139
	v_mov_b32_e32 v145, v143
	v_mov_b32_e32 v144, v142
	s_nop 0
	v_permlane32_swap_b32_e32 v143, v145
	v_permlane32_swap_b32_e32 v142, v144
	v_pk_add_f32 v[138:139], v[142:143], v[144:145]
	v_mov_b32_e32 v141, v136
	v_pk_fma_f32 v[138:139], v[138:139], s[4:5], v[182:183] op_sel_hi:[1,0,0]
	s_nop 0
	v_mul_f32_e32 v140, 0x4b800000, v139
	v_cmp_gt_f32_e64 s[44:45], s50, v139
	v_cmp_gt_f32_e32 vcc, s50, v138
	s_nop 0
	v_cndmask_b32_e64 v139, v139, v140, s[44:45]
	v_rsq_f32_e32 v139, v139
	s_nop 0
	v_mul_f32_e32 v140, 0x45800000, v139
	v_cndmask_b32_e64 v139, v139, v140, s[44:45]
	v_mul_f32_e32 v140, 0x4b800000, v138
	v_cndmask_b32_e32 v138, v138, v140, vcc
	v_rsq_f32_e32 v138, v138
	s_nop 0
	v_mul_f32_e32 v140, 0x45800000, v138
	v_cndmask_b32_e32 v138, v138, v140, vcc
	v_mov_b32_e32 v140, v135
	v_mov_b32_e32 v135, v137
	v_pk_add_f32 v[134:135], v[140:141], v[134:135]
	v_mov_b32_e32 v140, v131
	v_mov_b32_e32 v141, v132
	v_mov_b32_e32 v131, v133
	v_pk_add_f32 v[130:131], v[140:141], v[130:131]
	v_pk_add_f32 v[134:135], v[134:135], v[134:135] op_sel:[0,1] op_sel_hi:[1,0]
	v_pk_add_f32 v[130:131], v[130:131], v[130:131] op_sel:[0,1] op_sel_hi:[1,0]
	v_mov_b32_e32 v135, v134
	v_mov_b32_e32 v131, v130
	s_nop 0
	v_permlane16_swap_b32_e32 v134, v135
	v_permlane16_swap_b32_e32 v130, v131
	v_add_f32_e32 v135, v134, v135
	v_add_f32_e32 v134, v130, v131
	v_mov_b32_e32 v137, v135
	v_mov_b32_e32 v136, v134
	s_nop 0
	v_permlane32_swap_b32_e32 v135, v137
	v_permlane32_swap_b32_e32 v134, v136
	v_pk_add_f32 v[130:131], v[134:135], v[136:137]
	v_mul_f32_e32 v135, 0xbfb8aa3b, v169
	v_mul_f32_e32 v136, v122, v135
	v_mul_f32_e32 v137, v123, v135
	v_exp_f32_e32 v136, v136
	v_exp_f32_e32 v137, v137
	v_pk_fma_f32 v[130:131], v[130:131], s[4:5], v[182:183] op_sel_hi:[1,0,0]
	v_mul_f32_e32 v134, v169, v169
	v_add_f32_e32 v136, 1.0, v136
	v_add_f32_e32 v137, 1.0, v137
	v_rcp_f32_e32 v136, v136
	v_rcp_f32_e32 v137, v137
	v_mul_f32_e32 v132, 0x4b800000, v131
	v_cmp_gt_f32_e64 s[44:45], s50, v131
	v_pk_mul_f32 v[122:123], v[126:127], v[122:123]
	v_pk_mul_f32 v[126:127], v[134:135], v[136:137] op_sel_hi:[0,1]
	v_cndmask_b32_e64 v131, v131, v132, s[44:45]
	v_rsq_f32_e32 v131, v131
	v_pk_mul_f32 v[122:123], v[122:123], v[126:127]
	v_mul_f32_e32 v126, v114, v135
	v_mul_f32_e32 v127, v115, v135
	v_exp_f32_e32 v126, v126
	v_exp_f32_e32 v127, v127
	v_mul_f32_e32 v116, v116, v135
	v_mul_f32_e32 v117, v117, v135
	v_mul_f32_e32 v124, v124, v135
	v_mul_f32_e32 v125, v125, v135
	v_exp_f32_e32 v116, v116
	v_exp_f32_e32 v117, v117
	v_mul_f32_e32 v132, 0x45800000, v131
	v_exp_f32_e32 v124, v124
	v_exp_f32_e32 v125, v125
	v_cmp_gt_f32_e32 vcc, s50, v130
	v_cndmask_b32_e64 v131, v131, v132, s[44:45]
	v_mul_f32_e32 v132, 0x4b800000, v130
	v_cndmask_b32_e32 v130, v130, v132, vcc
	v_add_f32_e32 v126, 1.0, v126
	v_add_f32_e32 v127, 1.0, v127
	v_rsq_f32_e32 v130, v130
	v_rcp_f32_e32 v126, v126
	v_rcp_f32_e32 v127, v127
	v_add_f32_e32 v116, 1.0, v116
	v_add_f32_e32 v117, 1.0, v117
	v_add_f32_e32 v124, 1.0, v124
	v_add_f32_e32 v125, 1.0, v125
	v_rcp_f32_e32 v116, v116
	v_rcp_f32_e32 v117, v117
	v_rcp_f32_e32 v124, v124
	v_rcp_f32_e32 v125, v125
	v_mul_f32_e32 v132, 0x45800000, v130
	v_pk_mul_f32 v[114:115], v[118:119], v[114:115]
	v_pk_mul_f32 v[118:119], v[134:135], v[126:127] op_sel_hi:[0,1]
	v_cndmask_b32_e32 v130, v130, v132, vcc
	v_lshl_or_b32 v132, s14, 7, v186
	v_pk_mul_f32 v[114:115], v[114:115], v[118:119]
	v_pk_mul_f32 v[116:117], v[134:135], v[116:117] op_sel_hi:[0,1]
	v_ashrrev_i32_e32 v133, 31, v132
	v_pk_mul_f32 v[124:125], v[134:135], v[124:125] op_sel_hi:[0,1]
	v_pk_mul_f32 v[116:117], v[120:121], v[116:117]
	v_cvt_pk_bf16_f32 v120, v114, v115
	v_mov_b64_e32 v[114:115], s[70:71]
	v_pk_mul_f32 v[124:125], v[128:129], v[124:125]
	v_cvt_pk_bf16_f32 v118, v122, v123
	v_cvt_pk_bf16_f32 v121, v116, v117
	v_mad_i64_i32 v[122:123], s[0:1], v180, s97, v[114:115]
	v_lshlrev_b64 v[116:117], 1, v[132:133]
	v_cvt_pk_bf16_f32 v119, v124, v125
	v_lshl_add_u64 v[122:123], v[122:123], 0, v[116:117]
	global_store_dwordx4 v[122:123], v[118:121], off
	s_and_b64 vcc, exec, s[42:43]
	s_nop 0
	v_mul_f32_e32 v119, 0xbfb8aa3b, v167
	v_mul_f32_e32 v120, v106, v119
	v_mul_f32_e32 v121, v107, v119
	v_exp_f32_e32 v120, v120
	v_exp_f32_e32 v121, v121
	v_mul_f32_e32 v118, v167, v167
	v_pk_mul_f32 v[106:107], v[110:111], v[106:107]
	v_add_f32_e32 v120, 1.0, v120
	v_add_f32_e32 v121, 1.0, v121
	v_rcp_f32_e32 v120, v120
	v_rcp_f32_e32 v121, v121
	v_mul_f32_e32 v108, v108, v119
	v_mul_f32_e32 v109, v109, v119
	v_exp_f32_e32 v108, v108
	v_pk_mul_f32 v[110:111], v[118:119], v[120:121] op_sel_hi:[0,1]
	v_pk_mul_f32 v[106:107], v[106:107], v[110:111]
	v_mul_f32_e32 v110, v98, v119
	v_mul_f32_e32 v111, v99, v119
	v_exp_f32_e32 v110, v110
	v_exp_f32_e32 v111, v111
	v_pk_mul_f32 v[98:99], v[102:103], v[98:99]
	v_exp_f32_e32 v109, v109
	v_add_f32_e32 v110, 1.0, v110
	v_add_f32_e32 v111, 1.0, v111
	v_rcp_f32_e32 v110, v110
	v_rcp_f32_e32 v111, v111
	v_add_f32_e32 v108, 1.0, v108
	v_add_f32_e32 v109, 1.0, v109
	v_rcp_f32_e32 v108, v108
	v_pk_mul_f32 v[102:103], v[118:119], v[110:111] op_sel_hi:[0,1]
	v_pk_mul_f32 v[102:103], v[98:99], v[102:103]
	v_mul_f32_e32 v98, v100, v119
	v_mul_f32_e32 v99, v101, v119
	v_exp_f32_e32 v98, v98
	v_exp_f32_e32 v99, v99
	v_rcp_f32_e32 v109, v109
	v_cvt_pk_bf16_f32 v100, v102, v103
	v_add_f32_e32 v98, 1.0, v98
	v_add_f32_e32 v99, 1.0, v99
	v_rcp_f32_e32 v98, v98
	v_rcp_f32_e32 v99, v99
; __device__ __forceinline__ unsigned cvtpk(float lo, float hi) { f32x2_t v = {lo, hi}; bf16x2_t b = __builtin_convertvector(v, bf16x2_t); return __builtin_bit_cast(unsigned, b); }
;     __device__ __forceinline__ void operator()(const AccT& acc, const Unit& u, int wr, int wc, int fr, int fq) const {
;     ...
;             for (int m = 0; m < 4; ++m) { const int row = row0 + ai * 128 + m * 16; const float rs = rsv[ai][m]; const float c1 = -rs * LOG2E, c2 = rs * rs;
;                 float a[8];
; #pragma unroll
;                 for (int n = 0; n < 2; ++n)
; #pragma unroll
;                     for (int j = 0; j < 4; ++j) { const float g_ = acc[ai][0][m][n][j]; a[n * 4 + j] = (g_ * acc[ai][1][m][n][j]) * (c2 * __builtin_amdgcn_rcpf(1.0f + __builtin_amdgcn_exp2f(g_ * c1))); }
;                 u32x4 w; w.x = cvtpk(a[0], a[1]); w.y = cvtpk(a[2], a[3]); w.z = cvtpk(a[4], a[5]); w.w = cvtpk(a[6], a[7]);
;                 *(u32x4*)(O + (size_t)row * DFF + col0) = w; }
	v_pk_mul_f32 v[108:109], v[118:119], v[108:109] op_sel_hi:[0,1]
	v_pk_mul_f32 v[108:109], v[112:113], v[108:109]
	v_mad_i64_i32 v[102:103], s[0:1], v178, s97, v[114:115]
	v_pk_mul_f32 v[98:99], v[118:119], v[98:99] op_sel_hi:[0,1]
	v_pk_mul_f32 v[104:105], v[104:105], v[98:99]
	v_cvt_pk_bf16_f32 v98, v106, v107
	v_cvt_pk_bf16_f32 v99, v108, v109
	v_cvt_pk_bf16_f32 v101, v104, v105
	v_lshl_add_u64 v[102:103], v[102:103], 0, v[116:117]
	global_store_dwordx4 v[102:103], v[98:101], off
	s_nop 1
	v_mul_f32_e32 v99, 0xbfb8aa3b, v147
	v_mul_f32_e32 v100, v90, v99
	v_mul_f32_e32 v101, v91, v99
	v_exp_f32_e32 v100, v100
	v_exp_f32_e32 v101, v101
	v_mul_f32_e32 v98, v147, v147
	v_pk_mul_f32 v[90:91], v[94:95], v[90:91]
	v_add_f32_e32 v100, 1.0, v100
	v_add_f32_e32 v101, 1.0, v101
	v_rcp_f32_e32 v100, v100
	v_rcp_f32_e32 v101, v101
	v_mul_f32_e32 v92, v92, v99
	v_mul_f32_e32 v93, v93, v99
	v_exp_f32_e32 v92, v92
	v_pk_mul_f32 v[94:95], v[98:99], v[100:101] op_sel_hi:[0,1]
	v_pk_mul_f32 v[90:91], v[90:91], v[94:95]
	v_mul_f32_e32 v94, v82, v99
	v_mul_f32_e32 v95, v83, v99
	v_exp_f32_e32 v94, v94
	v_exp_f32_e32 v95, v95
	v_pk_mul_f32 v[82:83], v[86:87], v[82:83]
	v_exp_f32_e32 v93, v93
	v_add_f32_e32 v94, 1.0, v94
	v_add_f32_e32 v95, 1.0, v95
	v_rcp_f32_e32 v94, v94
	v_rcp_f32_e32 v95, v95
	v_add_f32_e32 v92, 1.0, v92
	v_add_f32_e32 v93, 1.0, v93
	v_rcp_f32_e32 v92, v92
	v_pk_mul_f32 v[86:87], v[98:99], v[94:95] op_sel_hi:[0,1]
	v_pk_mul_f32 v[86:87], v[82:83], v[86:87]
	v_mul_f32_e32 v82, v84, v99
	v_mul_f32_e32 v83, v85, v99
	v_exp_f32_e32 v82, v82
	v_exp_f32_e32 v83, v83
	v_rcp_f32_e32 v93, v93
	v_cvt_pk_bf16_f32 v84, v86, v87
	v_add_f32_e32 v82, 1.0, v82
	v_add_f32_e32 v83, 1.0, v83
	v_rcp_f32_e32 v82, v82
	v_rcp_f32_e32 v83, v83
	v_pk_mul_f32 v[92:93], v[98:99], v[92:93] op_sel_hi:[0,1]
	v_pk_mul_f32 v[92:93], v[96:97], v[92:93]
	v_mad_i64_i32 v[86:87], s[0:1], v176, s97, v[114:115]
	v_pk_mul_f32 v[82:83], v[98:99], v[82:83] op_sel_hi:[0,1]
	v_pk_mul_f32 v[88:89], v[88:89], v[82:83]
	v_cvt_pk_bf16_f32 v82, v90, v91
	v_cvt_pk_bf16_f32 v83, v92, v93
	v_cvt_pk_bf16_f32 v85, v88, v89
	v_lshl_add_u64 v[86:87], v[86:87], 0, v[116:117]
	global_store_dwordx4 v[86:87], v[82:85], off
	s_nop 1
	v_mul_f32_e32 v83, 0xbfb8aa3b, v146
	v_mul_f32_e32 v84, v74, v83
	v_mul_f32_e32 v85, v75, v83
	v_exp_f32_e32 v84, v84
	v_exp_f32_e32 v85, v85
	v_mul_f32_e32 v82, v146, v146
	v_pk_mul_f32 v[74:75], v[78:79], v[74:75]
	v_add_f32_e32 v84, 1.0, v84
	v_add_f32_e32 v85, 1.0, v85
	v_rcp_f32_e32 v84, v84
	v_rcp_f32_e32 v85, v85
	v_mul_f32_e32 v76, v76, v83
	v_mul_f32_e32 v77, v77, v83
	v_exp_f32_e32 v76, v76
	v_pk_mul_f32 v[78:79], v[82:83], v[84:85] op_sel_hi:[0,1]
	v_pk_mul_f32 v[74:75], v[74:75], v[78:79]
	v_mul_f32_e32 v78, v66, v83
	v_mul_f32_e32 v79, v67, v83
	v_exp_f32_e32 v78, v78
	v_exp_f32_e32 v79, v79
	v_pk_mul_f32 v[66:67], v[70:71], v[66:67]
	v_exp_f32_e32 v77, v77
	v_add_f32_e32 v78, 1.0, v78
	v_add_f32_e32 v79, 1.0, v79
	v_rcp_f32_e32 v78, v78
	v_rcp_f32_e32 v79, v79
	v_add_f32_e32 v76, 1.0, v76
	v_add_f32_e32 v77, 1.0, v77
	v_rcp_f32_e32 v76, v76
	v_pk_mul_f32 v[70:71], v[82:83], v[78:79] op_sel_hi:[0,1]
	v_pk_mul_f32 v[70:71], v[66:67], v[70:71]
	v_mul_f32_e32 v66, v68, v83
	v_mul_f32_e32 v67, v69, v83
	v_exp_f32_e32 v66, v66
	v_exp_f32_e32 v67, v67
	v_rcp_f32_e32 v77, v77
	v_cvt_pk_bf16_f32 v68, v70, v71
	v_add_f32_e32 v66, 1.0, v66
	v_add_f32_e32 v67, 1.0, v67
	v_rcp_f32_e32 v66, v66
	v_rcp_f32_e32 v67, v67
	v_pk_mul_f32 v[76:77], v[82:83], v[76:77] op_sel_hi:[0,1]
	v_pk_mul_f32 v[76:77], v[80:81], v[76:77]
	v_mad_i64_i32 v[70:71], s[0:1], v174, s97, v[114:115]
	v_pk_mul_f32 v[66:67], v[82:83], v[66:67] op_sel_hi:[0,1]
	v_pk_mul_f32 v[72:73], v[72:73], v[66:67]
	v_cvt_pk_bf16_f32 v66, v74, v75
	v_cvt_pk_bf16_f32 v67, v76, v77
	v_cvt_pk_bf16_f32 v69, v72, v73
	v_lshl_add_u64 v[70:71], v[70:71], 0, v[116:117]
	global_store_dwordx4 v[70:71], v[66:69], off
	s_nop 1
	v_mul_f32_e32 v67, 0xbfb8aa3b, v139
	v_mul_f32_e32 v68, v58, v67
	v_mul_f32_e32 v69, v59, v67
	v_exp_f32_e32 v68, v68
	v_exp_f32_e32 v69, v69
	v_mul_f32_e32 v66, v139, v139
	v_pk_mul_f32 v[58:59], v[62:63], v[58:59]
	v_add_f32_e32 v68, 1.0, v68
	v_add_f32_e32 v69, 1.0, v69
	v_rcp_f32_e32 v68, v68
	v_rcp_f32_e32 v69, v69
	v_mul_f32_e32 v60, v60, v67
	v_mul_f32_e32 v61, v61, v67
	v_exp_f32_e32 v60, v60
	v_pk_mul_f32 v[62:63], v[66:67], v[68:69] op_sel_hi:[0,1]
	v_pk_mul_f32 v[58:59], v[58:59], v[62:63]
	v_mul_f32_e32 v62, v50, v67
	v_mul_f32_e32 v63, v51, v67
	v_exp_f32_e32 v62, v62
	v_exp_f32_e32 v63, v63
	v_pk_mul_f32 v[50:51], v[54:55], v[50:51]
	v_exp_f32_e32 v61, v61
	v_add_f32_e32 v62, 1.0, v62
	v_add_f32_e32 v63, 1.0, v63
	v_rcp_f32_e32 v62, v62
	v_rcp_f32_e32 v63, v63
	v_add_f32_e32 v60, 1.0, v60
	v_add_f32_e32 v61, 1.0, v61
	v_rcp_f32_e32 v60, v60
	v_pk_mul_f32 v[54:55], v[66:67], v[62:63] op_sel_hi:[0,1]
	v_pk_mul_f32 v[54:55], v[50:51], v[54:55]
	v_mul_f32_e32 v50, v52, v67
	v_mul_f32_e32 v51, v53, v67
	v_exp_f32_e32 v50, v50
	v_exp_f32_e32 v51, v51
	v_rcp_f32_e32 v61, v61
	v_cvt_pk_bf16_f32 v52, v54, v55
	v_add_f32_e32 v50, 1.0, v50
	v_add_f32_e32 v51, 1.0, v51
	v_rcp_f32_e32 v50, v50
	v_rcp_f32_e32 v51, v51
	v_pk_mul_f32 v[60:61], v[66:67], v[60:61] op_sel_hi:[0,1]
	v_pk_mul_f32 v[60:61], v[64:65], v[60:61]
	v_mad_i64_i32 v[54:55], s[0:1], v172, s97, v[114:115]
	v_pk_mul_f32 v[50:51], v[66:67], v[50:51] op_sel_hi:[0,1]
	v_pk_mul_f32 v[56:57], v[56:57], v[50:51]
; __device__ __forceinline__ unsigned cvtpk(float lo, float hi) { f32x2_t v = {lo, hi}; bf16x2_t b = __builtin_convertvector(v, bf16x2_t); return __builtin_bit_cast(unsigned, b); }
; #define PG8_BAR __builtin_amdgcn_s_barrier()
; template <class Epi, class Sched>
; __device__ __forceinline__ void gemm_phase(LAS unsigned char* lds, const Gemm g, const Sched& S, const Epi& E) {
;     ...
;         if (!has_next) break;
; #pragma unroll
;         for (int a = 0; a < 2; ++a)
; #pragma unroll
;             for (int b = 0; b < 2; ++b)
; #pragma unroll
;                 for (int m = 0; m < 4; ++m)
; #pragma unroll
;                     for (int n = 0; n < 2; ++n) acc[a][b][m][n] = (f32x4){0.f, 0.f, 0.f, 0.f};
;         cur = nxt; cA = nA; cB = nB; ++ui;
;         if (wr == 1) PG8_BAR;
;     __device__ __forceinline__ void operator()(const AccT& acc, const Unit& u, int wr, int wc, int fr, int fq) const {
;     ...
;             for (int m = 0; m < 4; ++m) { const int row = row0 + ai * 128 + m * 16; const float rs = rsv[ai][m]; const float c1 = -rs * LOG2E, c2 = rs * rs;
;                 float a[8];
; #pragma unroll
;                 for (int n = 0; n < 2; ++n)
; #pragma unroll
;                     for (int j = 0; j < 4; ++j) { const float g_ = acc[ai][0][m][n][j]; a[n * 4 + j] = (g_ * acc[ai][1][m][n][j]) * (c2 * __builtin_amdgcn_rcpf(1.0f + __builtin_amdgcn_exp2f(g_ * c1))); }
;                 u32x4 w; w.x = cvtpk(a[0], a[1]); w.y = cvtpk(a[2], a[3]); w.z = cvtpk(a[4], a[5]); w.w = cvtpk(a[6], a[7]);
;                 *(u32x4*)(O + (size_t)row * DFF + col0) = w; }
	v_cvt_pk_bf16_f32 v50, v58, v59
	v_cvt_pk_bf16_f32 v51, v60, v61
	v_cvt_pk_bf16_f32 v53, v56, v57
	v_lshl_add_u64 v[54:55], v[54:55], 0, v[116:117]
	global_store_dwordx4 v[54:55], v[50:53], off
	s_nop 1
	v_mul_f32_e32 v51, 0xbfb8aa3b, v138
	v_mul_f32_e32 v52, v42, v51
	v_mul_f32_e32 v53, v43, v51
	v_exp_f32_e32 v52, v52
	v_exp_f32_e32 v53, v53
	v_mul_f32_e32 v50, v138, v138
	v_pk_mul_f32 v[42:43], v[46:47], v[42:43]
	v_add_f32_e32 v52, 1.0, v52
	v_add_f32_e32 v53, 1.0, v53
	v_rcp_f32_e32 v52, v52
	v_rcp_f32_e32 v53, v53
	v_mul_f32_e32 v44, v44, v51
	v_mul_f32_e32 v45, v45, v51
	v_exp_f32_e32 v44, v44
	v_pk_mul_f32 v[46:47], v[50:51], v[52:53] op_sel_hi:[0,1]
	v_pk_mul_f32 v[42:43], v[42:43], v[46:47]
	v_mul_f32_e32 v46, v34, v51
	v_mul_f32_e32 v47, v35, v51
	v_exp_f32_e32 v46, v46
	v_exp_f32_e32 v47, v47
	v_pk_mul_f32 v[34:35], v[38:39], v[34:35]
	v_exp_f32_e32 v45, v45
	v_add_f32_e32 v46, 1.0, v46
	v_add_f32_e32 v47, 1.0, v47
	v_rcp_f32_e32 v46, v46
	v_rcp_f32_e32 v47, v47
	v_add_f32_e32 v44, 1.0, v44
	v_add_f32_e32 v45, 1.0, v45
	v_rcp_f32_e32 v44, v44
	v_pk_mul_f32 v[38:39], v[50:51], v[46:47] op_sel_hi:[0,1]
	v_pk_mul_f32 v[38:39], v[34:35], v[38:39]
	v_mul_f32_e32 v34, v36, v51
	v_mul_f32_e32 v35, v37, v51
	v_exp_f32_e32 v34, v34
	v_exp_f32_e32 v35, v35
	v_rcp_f32_e32 v45, v45
	v_cvt_pk_bf16_f32 v36, v38, v39
	v_add_f32_e32 v34, 1.0, v34
	v_add_f32_e32 v35, 1.0, v35
	v_rcp_f32_e32 v34, v34
	v_rcp_f32_e32 v35, v35
	v_pk_mul_f32 v[44:45], v[50:51], v[44:45] op_sel_hi:[0,1]
	v_pk_mul_f32 v[44:45], v[48:49], v[44:45]
	v_mad_i64_i32 v[38:39], s[0:1], v170, s97, v[114:115]
	v_pk_mul_f32 v[34:35], v[50:51], v[34:35] op_sel_hi:[0,1]
	v_pk_mul_f32 v[40:41], v[40:41], v[34:35]
	v_cvt_pk_bf16_f32 v34, v42, v43
	v_cvt_pk_bf16_f32 v35, v44, v45
	v_cvt_pk_bf16_f32 v37, v40, v41
	v_lshl_add_u64 v[38:39], v[38:39], 0, v[116:117]
	global_store_dwordx4 v[38:39], v[34:37], off
	s_nop 1
	v_mul_f32_e32 v35, 0xbfb8aa3b, v131
	v_mul_f32_e32 v36, v26, v35
	v_mul_f32_e32 v37, v27, v35
	v_exp_f32_e32 v36, v36
	v_exp_f32_e32 v37, v37
	v_mul_f32_e32 v34, v131, v131
	v_pk_mul_f32 v[26:27], v[30:31], v[26:27]
	v_add_f32_e32 v36, 1.0, v36
	v_add_f32_e32 v37, 1.0, v37
	v_rcp_f32_e32 v36, v36
	v_rcp_f32_e32 v37, v37
	v_mul_f32_e32 v28, v28, v35
	v_mul_f32_e32 v29, v29, v35
	v_exp_f32_e32 v28, v28
	v_pk_mul_f32 v[30:31], v[34:35], v[36:37] op_sel_hi:[0,1]
	v_pk_mul_f32 v[26:27], v[26:27], v[30:31]
	v_mul_f32_e32 v30, v18, v35
	v_mul_f32_e32 v31, v19, v35
	v_exp_f32_e32 v30, v30
	v_exp_f32_e32 v31, v31
	v_pk_mul_f32 v[18:19], v[22:23], v[18:19]
	v_exp_f32_e32 v29, v29
	v_add_f32_e32 v30, 1.0, v30
	v_add_f32_e32 v31, 1.0, v31
	v_rcp_f32_e32 v30, v30
	v_rcp_f32_e32 v31, v31
	v_add_f32_e32 v28, 1.0, v28
	v_add_f32_e32 v29, 1.0, v29
	v_rcp_f32_e32 v28, v28
	v_pk_mul_f32 v[22:23], v[34:35], v[30:31] op_sel_hi:[0,1]
	v_pk_mul_f32 v[22:23], v[18:19], v[22:23]
	v_mul_f32_e32 v18, v20, v35
	v_mul_f32_e32 v19, v21, v35
	v_exp_f32_e32 v18, v18
	v_exp_f32_e32 v19, v19
	v_rcp_f32_e32 v29, v29
	v_cvt_pk_bf16_f32 v20, v22, v23
	v_add_f32_e32 v18, 1.0, v18
	v_add_f32_e32 v19, 1.0, v19
	v_rcp_f32_e32 v18, v18
	v_rcp_f32_e32 v19, v19
	v_pk_mul_f32 v[28:29], v[34:35], v[28:29] op_sel_hi:[0,1]
	v_pk_mul_f32 v[28:29], v[32:33], v[28:29]
	v_mad_i64_i32 v[22:23], s[0:1], v168, s97, v[114:115]
	v_pk_mul_f32 v[18:19], v[34:35], v[18:19] op_sel_hi:[0,1]
	v_pk_mul_f32 v[24:25], v[24:25], v[18:19]
	v_cvt_pk_bf16_f32 v18, v26, v27
	v_cvt_pk_bf16_f32 v19, v28, v29
	v_cvt_pk_bf16_f32 v21, v24, v25
	v_lshl_add_u64 v[22:23], v[22:23], 0, v[116:117]
	global_store_dwordx4 v[22:23], v[18:21], off
	s_nop 1
	v_mul_f32_e32 v19, 0xbfb8aa3b, v130
	v_mul_f32_e32 v20, v10, v19
	v_mul_f32_e32 v21, v11, v19
	v_exp_f32_e32 v20, v20
	v_exp_f32_e32 v21, v21
	v_mul_f32_e32 v18, v130, v130
	v_pk_mul_f32 v[10:11], v[14:15], v[10:11]
	v_add_f32_e32 v20, 1.0, v20
	v_add_f32_e32 v21, 1.0, v21
	v_rcp_f32_e32 v20, v20
	v_rcp_f32_e32 v21, v21
	v_mul_f32_e32 v12, v12, v19
	v_mul_f32_e32 v13, v13, v19
	v_exp_f32_e32 v12, v12
	v_pk_mul_f32 v[14:15], v[18:19], v[20:21] op_sel_hi:[0,1]
	v_pk_mul_f32 v[10:11], v[10:11], v[14:15]
	v_mul_f32_e32 v14, v2, v19
	v_mul_f32_e32 v15, v3, v19
	v_exp_f32_e32 v14, v14
	v_exp_f32_e32 v15, v15
	v_pk_mul_f32 v[2:3], v[6:7], v[2:3]
	v_exp_f32_e32 v13, v13
	v_add_f32_e32 v14, 1.0, v14
	v_add_f32_e32 v15, 1.0, v15
	v_rcp_f32_e32 v14, v14
	v_rcp_f32_e32 v15, v15
	v_add_f32_e32 v12, 1.0, v12
	v_add_f32_e32 v13, 1.0, v13
	v_rcp_f32_e32 v12, v12
	v_pk_mul_f32 v[6:7], v[18:19], v[14:15] op_sel_hi:[0,1]
	v_pk_mul_f32 v[6:7], v[2:3], v[6:7]
	v_mul_f32_e32 v2, v4, v19
	v_mul_f32_e32 v3, v5, v19
	v_exp_f32_e32 v2, v2
	v_exp_f32_e32 v3, v3
	v_rcp_f32_e32 v13, v13
	v_cvt_pk_bf16_f32 v4, v6, v7
	v_add_f32_e32 v2, 1.0, v2
	v_add_f32_e32 v3, 1.0, v3
	v_rcp_f32_e32 v2, v2
	v_rcp_f32_e32 v3, v3
	v_pk_mul_f32 v[12:13], v[18:19], v[12:13] op_sel_hi:[0,1]
	v_pk_mul_f32 v[12:13], v[16:17], v[12:13]
	v_mad_i64_i32 v[6:7], s[0:1], v166, s97, v[114:115]
	v_pk_mul_f32 v[2:3], v[18:19], v[2:3] op_sel_hi:[0,1]
	v_pk_mul_f32 v[8:9], v[8:9], v[2:3]
	v_cvt_pk_bf16_f32 v2, v10, v11
	v_cvt_pk_bf16_f32 v3, v12, v13
	v_cvt_pk_bf16_f32 v5, v8, v9
	v_lshl_add_u64 v[6:7], v[6:7], 0, v[116:117]
	s_mov_b64 s[0:1], -1
	global_store_dwordx4 v[6:7], v[2:5], off
	s_cbranch_vccnz .LBB0_1899
	s_andn2_b64 vcc, exec, s[40:41]
	s_cbranch_vccnz .LBB0_1898
	s_barrier
	s_branch .LBB0_1898
